# context differential / context attention units: each tile barrier followed by a second s_barrier (wave re-alignment), on top of nt epilogue stores
# speedup vs baseline: 1.0854x; 1.0053x over previous
.LBB0_830:
	s_ashr_i32 s2, s16, 3
	s_ashr_i32 s3, s2, 31
	s_bfe_u32 s17, s16, 0x20001
	s_lshl_b64 s[4:5], s[2:3], 8
	s_mul_i32 s7, s2, 0x208000
	s_mul_hi_i32 s6, s2, 0x208000
	s_add_u32 s7, s12, s7
	s_addc_u32 s8, s13, s6
	s_lshl_b32 s40, s17, 8
	s_add_u32 s6, s7, s40
	s_addc_u32 s7, s8, 0
	s_add_u32 s20, s6, 0xc00
	s_addc_u32 s21, s7, 0
	s_lshl_b32 s8, s17, 22
	s_add_u32 s8, s85, s8
	s_addc_u32 s9, s82, 0
	s_lshl_b64 s[2:3], s[2:3], 9
	s_add_u32 s8, s8, s2
	v_mov_b32_e32 v172, v206
	s_addc_u32 s9, s9, s3
	s_and_b32 s2, s11, 0x80
	v_mov_b32_e32 v10, v206
	v_readfirstlane_b32 s10, v172
	s_bfe_u32 s18, s10, 0x20006
	v_and_or_b32 v0, v172, 31, s2
	v_lshl_or_b32 v0, s18, 5, v0
	v_or_b32_e32 v174, s4, v0
	v_mov_b64_e32 v[0:1], s[12:13]
	s_ashr_i32 s19, s10, 8
	v_mad_u64_u32 v[146:147], s[2:3], v174, s79, v[0:1]
	v_mad_i32_i24 v147, s5, v211, v147
	s_lshl_b32 s2, s19, 6
	v_lshl_add_u64 v[0:1], v[146:147], 0, s[40:41]
	s_ashr_i32 s3, s2, 31
	v_lshl_add_u64 v[0:1], s[2:3], 1, v[0:1]
	v_lshrrev_b32_e32 v2, 1, v10
	v_and_b32_e32 v192, 16, v2
	v_lshl_add_u64 v[0:1], v[0:1], 0, v[192:193]
	v_lshlrev_b32_e32 v25, 4, v10
	flat_load_dwordx4 v[124:127], v[0:1] offset:2048
	flat_load_dwordx4 v[120:123], v[0:1] offset:2080
	flat_load_dwordx4 v[116:119], v[0:1] offset:2112
	flat_load_dwordx4 v[112:115], v[0:1] offset:2144
	v_and_b32_e32 v0, 0x70, v25
	v_mov_b32_e32 v1, v193
	v_lshl_add_u64 v[0:1], s[8:9], 0, v[0:1]
	s_mov_b64 s[8:9], 0x1000000
	v_lshl_add_u64 v[12:13], v[0:1], 0, s[8:9]
	v_ashrrev_i32_e32 v0, 31, v10
	v_lshrrev_b32_e32 v0, 28, v0
	v_add_u32_e32 v2, v10, v0
	v_ashrrev_i32_e32 v128, 4, v2
	v_and_b32_e32 v2, -16, v2
	v_add_u32_e32 v14, 0x200, v10
	v_readfirstlane_b32 s4, v10
	v_and_b32_e32 v32, 31, v10
	v_lshlrev_b32_e32 v24, 3, v10
	v_sub_u32_e32 v26, v10, v2
	v_ashrrev_i32_e32 v18, 3, v10
	v_ashrrev_i32_e32 v10, 31, v14
	v_lshrrev_b32_e32 v10, 28, v10
	v_lshlrev_b32_e32 v96, 3, v26
	v_add_u32_e32 v10, v14, v10
	v_mov_b64_e32 v[8:9], s[6:7]
	v_ashrrev_i32_e32 v97, 31, v96
	v_ashrrev_i32_e32 v19, 31, v18
	v_ashrrev_i32_e32 v129, 4, v10
	v_and_b32_e32 v10, -16, v10
	v_mad_i64_i32 v[0:1], s[8:9], v128, s79, v[8:9]
	v_lshlrev_b64 v[16:17], 1, v[96:97]
	v_lshlrev_b64 v[4:5], 15, v[18:19]
	v_sub_u32_e32 v19, v14, v10
	v_lshl_add_u64 v[0:1], v[0:1], 0, v[16:17]
	v_lshlrev_b32_e32 v100, 3, v19
	flat_load_dwordx4 v[0:3], v[0:1] offset:3072
	v_ashrrev_i32_e32 v101, 31, v100
	v_mad_i64_i32 v[8:9], s[8:9], v129, s79, v[8:9]
	v_lshlrev_b64 v[20:21], 1, v[100:101]
	v_ashrrev_i32_e32 v22, 3, v14
	v_lshl_add_u64 v[98:99], v[12:13], 0, v[4:5]
	v_lshl_add_u64 v[8:9], v[8:9], 0, v[20:21]
	v_ashrrev_i32_e32 v23, 31, v22
	flat_load_dwordx4 v[4:7], v[98:99]
	v_lshlrev_b64 v[14:15], 15, v[22:23]
	flat_load_dwordx4 v[8:11], v[8:9] offset:3072
	v_lshl_add_u64 v[102:103], v[12:13], 0, v[14:15]
	flat_load_dwordx4 v[12:15], v[102:103]
	v_and_b32_e32 v23, 0x60, v25
	v_and_b32_e32 v24, 8, v24
	s_movk_i32 s8, 0x110
	v_add3_u32 v130, 0, v23, v24
	v_mul_lo_u32 v23, v128, s8
	v_add_u32_e32 v23, 0, v23
	v_lshlrev_b32_e32 v24, 4, v26
	s_cmpk_gt_i32 s4, 0xff
	v_add_u32_e32 v177, v23, v24
	s_cselect_b64 s[2:3], -1, 0
	s_cmpk_lt_i32 s4, 0x100
	v_mul_lo_u32 v131, v18, s80
	v_mov_b32_e32 v173, s5
	s_cselect_b64 s[4:5], -1, 0
	v_add_u32_e32 v18, v130, v131
	v_add_u32_e32 v178, 0x8800, v18
	v_mul_lo_u32 v132, v22, s80
	v_mul_u32_u24_e32 v22, 0x110, v32
	s_mov_b32 s54, s41
	s_mov_b32 s55, s41
	s_mov_b32 s40, s41
	s_mov_b32 s42, s41
	s_mov_b32 s43, s41
	s_mov_b32 s44, s41
	s_mov_b32 s45, s41
	s_mov_b32 s46, s41
	s_mov_b32 s47, s41
	s_mov_b32 s48, s41
	s_mov_b32 s49, s41
	s_mov_b32 s50, s41
	s_mov_b32 s51, s41
	s_mov_b32 s52, s41
	s_mov_b32 s53, s41
	v_mov_b64_e32 v[62:63], s[54:55]
	v_add_u32_e32 v33, 0, v192
	v_mov_b64_e32 v[48:49], s[40:41]
	v_mov_b64_e32 v[60:61], s[52:53]
	v_mov_b64_e32 v[58:59], s[50:51]
	v_mov_b64_e32 v[56:57], s[48:49]
	v_mov_b64_e32 v[54:55], s[46:47]
	v_mov_b64_e32 v[52:53], s[44:45]
	v_mov_b64_e32 v[50:51], s[42:43]
	s_waitcnt vmcnt(0) lgkmcnt(0)
	ds_write_b128 v177, v[0:3]
	v_mul_lo_u32 v0, v129, s8
	v_add_u32_e32 v0, 0, v0
	v_lshlrev_b32_e32 v1, 4, v19
	s_add_u32 s8, s6, 0x82c00
	v_add_u32_e32 v180, v0, v1
	s_addc_u32 s9, s7, 0
	v_add_u32_e32 v19, v130, v132
	v_add_u32_e32 v179, 0x8800, v19
	ds_write2_b64 v178, v[4:5], v[6:7] offset1:2
	s_add_u32 s6, s6, 0x104c00
	ds_write_b128 v180, v[8:11]
	v_mov_b64_e32 v[8:9], s[8:9]
	v_mad_i64_i32 v[0:1], s[8:9], v128, s79, v[8:9]
	ds_write2_b64 v179, v[12:13], v[14:15] offset1:2
	v_lshl_add_u64 v[0:1], v[0:1], 0, v[16:17]
	v_mad_i64_i32 v[8:9], s[8:9], v129, s79, v[8:9]
	flat_load_dwordx4 v[0:3], v[0:1]
	s_nop 0
	flat_load_dwordx4 v[4:7], v[98:99] offset:128
	v_lshl_add_u64 v[8:9], v[8:9], 0, v[20:21]
	flat_load_dwordx4 v[8:11], v[8:9]
	s_nop 0
	flat_load_dwordx4 v[12:15], v[102:103] offset:128
	s_waitcnt lgkmcnt(0)
	s_barrier
	s_barrier
	s_addc_u32 s7, s7, 0
	s_and_b64 vcc, exec, s[2:3]
	s_waitcnt vmcnt(0)
	ds_write_b128 v177, v[0:3] offset:17408
	v_add_u32_e32 v0, 0xd000, v18
	ds_write2_b64 v0, v[4:5], v[6:7] offset1:2
	ds_write_b128 v180, v[8:11] offset:17408
	v_add_u32_e32 v0, 0xd000, v19
	ds_write2_b64 v0, v[12:13], v[14:15] offset1:2
	v_mov_b64_e32 v[0:1], s[6:7]
	v_mad_i64_i32 v[2:3], s[6:7], v128, s79, v[0:1]
	v_mad_i64_i32 v[0:1], s[6:7], v129, s79, v[0:1]
	v_lshl_add_u64 v[2:3], v[2:3], 0, v[16:17]
	v_lshl_add_u64 v[0:1], v[0:1], 0, v[20:21]
	flat_load_dwordx4 v[76:79], v[2:3]
	flat_load_dwordx4 v[68:71], v[98:99] offset:256
	flat_load_dwordx4 v[72:75], v[0:1]
	flat_load_dwordx4 v[64:67], v[102:103] offset:256
	s_lshl_b32 s6, s19, 7
	s_add_i32 s6, s6, 0
	v_add3_u32 v176, s6, v22, v192
	ds_read_b128 v[16:19], v176 offset:8704
	ds_read_b128 v[0:3], v176
	ds_read_b128 v[34:37], v176 offset:32
	s_waitcnt lgkmcnt(0)
	v_mfma_f32_32x32x16_bf16 v[0:15], v[0:3], v[124:127], 0
	ds_read_b128 v[38:41], v176 offset:8736
	v_mfma_f32_32x32x16_bf16 v[16:31], v[16:19], v[124:127], 0
	v_mfma_f32_32x32x16_bf16 v[0:15], v[34:37], v[120:123], v[0:15]
	s_waitcnt lgkmcnt(0)
	v_mfma_f32_32x32x16_bf16 v[16:31], v[38:41], v[120:123], v[16:31]
	ds_read_b128 v[34:37], v176 offset:8768
	ds_read_b128 v[38:41], v176 offset:64
	s_waitcnt lgkmcnt(0)
	v_mfma_f32_32x32x16_bf16 v[0:15], v[38:41], v[116:119], v[0:15]
	v_mfma_f32_32x32x16_bf16 v[16:31], v[34:37], v[116:119], v[16:31]
	ds_read_b128 v[34:37], v176 offset:8800
	ds_read_b128 v[38:41], v176 offset:96
	s_waitcnt lgkmcnt(0)
	v_mfma_f32_32x32x16_bf16 v[0:15], v[38:41], v[112:115], v[0:15]
	v_mfma_f32_32x32x16_bf16 v[16:31], v[34:37], v[112:115], v[16:31]
	s_nop 10
	v_max_f32_e32 v34, v1, v1
	v_max_f32_e32 v35, v0, v0
	v_max_f32_e32 v34, v35, v34
	v_max3_f32 v35, v2, v3, v17
	v_max3_f32 v34, v34, v16, v18
	v_max3_f32 v34, v34, v19, v4
	v_max3_f32 v35, v35, v6, v7
	v_max3_f32 v34, v34, v5, v20
	v_max3_f32 v35, v35, v22, v23
	v_max3_f32 v34, v34, v21, v8
	v_max3_f32 v35, v35, v10, v11
	v_max3_f32 v34, v34, v9, v24
	v_max3_f32 v35, v35, v26, v27
	v_max3_f32 v34, v34, v25, v12
	v_max3_f32 v35, v35, v14, v15
	v_max3_f32 v34, v34, v13, v28
	v_max3_f32 v35, v35, v30, v31
	v_max3_f32 v34, v34, v29, v35
	v_mov_b32_e32 v35, v34
	s_nop 1
	v_permlane32_swap_b32_e32 v34, v35
	v_max_f32_e32 v35, v35, v35
	v_max_f32_e32 v34, v34, v34
	v_max_f32_e32 v181, v34, v35
	v_sub_f32_e32 v0, v0, v181
	v_sub_f32_e32 v16, v16, v181
	v_sub_f32_e32 v1, v1, v181
	v_sub_f32_e32 v17, v17, v181
	v_sub_f32_e32 v2, v2, v181
	v_sub_f32_e32 v18, v18, v181
	v_sub_f32_e32 v3, v3, v181
	v_sub_f32_e32 v19, v19, v181
	v_sub_f32_e32 v4, v4, v181
	v_sub_f32_e32 v20, v20, v181
	v_sub_f32_e32 v5, v5, v181
	v_sub_f32_e32 v21, v21, v181
	v_sub_f32_e32 v6, v6, v181
	v_sub_f32_e32 v22, v22, v181
	v_sub_f32_e32 v7, v7, v181
	v_sub_f32_e32 v23, v23, v181
	v_sub_f32_e32 v8, v8, v181
	v_sub_f32_e32 v24, v24, v181
	v_sub_f32_e32 v9, v9, v181
	v_sub_f32_e32 v25, v25, v181
	v_sub_f32_e32 v10, v10, v181
	v_sub_f32_e32 v26, v26, v181
	v_sub_f32_e32 v11, v11, v181
	v_sub_f32_e32 v27, v27, v181
	v_sub_f32_e32 v12, v12, v181
	v_sub_f32_e32 v28, v28, v181
	v_sub_f32_e32 v13, v13, v181
	v_sub_f32_e32 v29, v29, v181
	v_sub_f32_e32 v14, v14, v181
	v_sub_f32_e32 v30, v30, v181
	v_sub_f32_e32 v15, v15, v181
	v_sub_f32_e32 v31, v31, v181
	v_exp_f32_e32 v104, v0
	v_exp_f32_e32 v105, v1
	v_exp_f32_e32 v106, v16
	v_exp_f32_e32 v107, v17
	v_exp_f32_e32 v108, v2
	v_exp_f32_e32 v109, v3
	v_exp_f32_e32 v110, v18
	v_exp_f32_e32 v111, v19
	v_exp_f32_e32 v148, v4
	v_exp_f32_e32 v149, v5
	v_exp_f32_e32 v150, v20
	v_exp_f32_e32 v151, v21
	v_exp_f32_e32 v152, v6
	v_exp_f32_e32 v153, v7
	v_exp_f32_e32 v154, v22
	v_exp_f32_e32 v155, v23
	v_exp_f32_e32 v156, v8
	v_exp_f32_e32 v157, v9
	v_exp_f32_e32 v158, v24
	v_exp_f32_e32 v159, v25
	v_exp_f32_e32 v160, v10
	v_exp_f32_e32 v161, v11
	v_exp_f32_e32 v162, v26
	v_exp_f32_e32 v163, v27
	v_exp_f32_e32 v164, v12
	v_exp_f32_e32 v165, v13
	v_exp_f32_e32 v166, v28
	v_exp_f32_e32 v167, v29
	v_exp_f32_e32 v168, v14
	v_exp_f32_e32 v169, v15
	v_exp_f32_e32 v170, v30
	v_exp_f32_e32 v171, v31
	v_mul_u32_u24_e32 v0, 0x90, v32
	v_add_u32_e32 v175, v33, v0
	v_mov_b64_e32 v[32:33], v[48:49]
	v_mov_b64_e32 v[16:17], v[48:49]
	v_mov_b64_e32 v[0:1], v[48:49]
	v_cvt_pk_bf16_f32 v84, v104, v105
	v_cvt_pk_bf16_f32 v85, v108, v109
	v_cvt_pk_bf16_f32 v86, v148, v149
	v_cvt_pk_bf16_f32 v87, v152, v153
	v_cvt_pk_bf16_f32 v80, v106, v107
	v_cvt_pk_bf16_f32 v81, v110, v111
	v_cvt_pk_bf16_f32 v82, v150, v151
	v_cvt_pk_bf16_f32 v83, v154, v155
	v_cvt_pk_bf16_f32 v92, v156, v157
	v_cvt_pk_bf16_f32 v93, v160, v161
	v_cvt_pk_bf16_f32 v94, v164, v165
	v_cvt_pk_bf16_f32 v95, v168, v169
	v_cvt_pk_bf16_f32 v88, v158, v159
	v_cvt_pk_bf16_f32 v89, v162, v163
	v_cvt_pk_bf16_f32 v90, v166, v167
	v_cvt_pk_bf16_f32 v91, v170, v171
	v_mov_b64_e32 v[34:35], v[50:51]
	v_mov_b64_e32 v[36:37], v[52:53]
	v_mov_b64_e32 v[38:39], v[54:55]
	v_mov_b64_e32 v[40:41], v[56:57]
	v_mov_b64_e32 v[42:43], v[58:59]
	v_mov_b64_e32 v[44:45], v[60:61]
	v_mov_b64_e32 v[46:47], v[62:63]
	v_mov_b64_e32 v[18:19], v[50:51]
	v_mov_b64_e32 v[20:21], v[52:53]
	v_mov_b64_e32 v[22:23], v[54:55]
	v_mov_b64_e32 v[24:25], v[56:57]
	v_mov_b64_e32 v[26:27], v[58:59]
	v_mov_b64_e32 v[28:29], v[60:61]
	v_mov_b64_e32 v[30:31], v[62:63]
	v_mov_b64_e32 v[2:3], v[50:51]
	v_mov_b64_e32 v[4:5], v[52:53]
	v_mov_b64_e32 v[6:7], v[54:55]
	v_mov_b64_e32 v[8:9], v[56:57]
	v_mov_b64_e32 v[10:11], v[58:59]
	v_mov_b64_e32 v[12:13], v[60:61]
	v_mov_b64_e32 v[14:15], v[62:63]
	s_cbranch_vccnz .LBB0_832
	ds_read_b128 v[0:3], v175 offset:34816
	ds_read_b128 v[4:7], v175 offset:34848
	s_waitcnt lgkmcnt(0)
	v_mfma_f32_32x32x16_bf16 v[48:63], v[0:3], v[84:87], 0
	ds_read_b128 v[0:3], v175 offset:34880
	ds_read_b128 v[134:137], v175 offset:48672
	v_mfma_f32_32x32x16_bf16 v[48:63], v[4:7], v[92:95], v[48:63]
	s_waitcnt lgkmcnt(0)
	v_mfma_f32_32x32x16_bf16 v[48:63], v[0:3], v[80:83], v[48:63]
	ds_read_b128 v[0:3], v175 offset:34912
	s_waitcnt lgkmcnt(0)
	v_mfma_f32_32x32x16_bf16 v[48:63], v[0:3], v[88:91], v[48:63]
	ds_read_b128 v[0:3], v175 offset:39424
	s_waitcnt lgkmcnt(0)
	v_mfma_f32_32x32x16_bf16 v[32:47], v[0:3], v[84:87], 0
	ds_read_b128 v[0:3], v175 offset:39456
	s_waitcnt lgkmcnt(0)
	v_mfma_f32_32x32x16_bf16 v[32:47], v[0:3], v[92:95], v[32:47]
	ds_read_b128 v[0:3], v175 offset:39488
	s_waitcnt lgkmcnt(0)
	v_mfma_f32_32x32x16_bf16 v[32:47], v[0:3], v[80:83], v[32:47]
	ds_read_b128 v[0:3], v175 offset:39520
	s_waitcnt lgkmcnt(0)
	v_mfma_f32_32x32x16_bf16 v[32:47], v[0:3], v[88:91], v[32:47]
	ds_read_b128 v[0:3], v175 offset:44032
	s_waitcnt lgkmcnt(0)
	v_mfma_f32_32x32x16_bf16 v[16:31], v[0:3], v[84:87], 0
	ds_read_b128 v[0:3], v175 offset:44064
	s_waitcnt lgkmcnt(0)
	v_mfma_f32_32x32x16_bf16 v[16:31], v[0:3], v[92:95], v[16:31]
	ds_read_b128 v[0:3], v175 offset:44096
	s_waitcnt lgkmcnt(0)
	v_mfma_f32_32x32x16_bf16 v[16:31], v[0:3], v[80:83], v[16:31]
	ds_read_b128 v[0:3], v175 offset:44128
	s_waitcnt lgkmcnt(0)
	v_mfma_f32_32x32x16_bf16 v[16:31], v[0:3], v[88:91], v[16:31]
	ds_read_b128 v[0:3], v175 offset:48640
	s_waitcnt lgkmcnt(0)
	v_mfma_f32_32x32x16_bf16 v[0:15], v[0:3], v[84:87], 0
	v_mfma_f32_32x32x16_bf16 v[0:15], v[134:137], v[92:95], v[0:15]
	ds_read_b128 v[134:137], v175 offset:48704
	s_waitcnt lgkmcnt(0)
	v_mfma_f32_32x32x16_bf16 v[0:15], v[134:137], v[80:83], v[0:15]
	ds_read_b128 v[134:137], v175 offset:48736
	s_waitcnt lgkmcnt(0)
	v_mfma_f32_32x32x16_bf16 v[0:15], v[134:137], v[88:91], v[0:15]
.LBB0_832:
	v_add_u32_e32 v130, 0x8800, v130
	s_waitcnt lgkmcnt(0)
	s_barrier
	s_barrier
	s_waitcnt vmcnt(0)
	ds_write_b128 v177, v[76:79]
	v_add_u32_e32 v76, v130, v131
	v_mad_i64_i32 v[134:135], s[6:7], v128, s79, 0
	v_mad_i64_i32 v[128:129], s[6:7], v129, s79, 0
	v_add_u32_e32 v76, 0x9000, v76
	ds_write2_b64 v76, v[68:69], v[70:71] offset1:2
	ds_write_b128 v180, v[72:75]
	v_add_u32_e32 v68, v130, v132
	s_add_u32 s6, s20, 0x186000
	v_add_u32_e32 v68, 0x9000, v68
	s_addc_u32 s7, s21, 0
	ds_write2_b64 v68, v[64:65], v[66:67] offset1:2
	v_lshl_add_u64 v[64:65], s[6:7], 0, v[134:135]
	v_lshl_add_u64 v[64:65], v[96:97], 1, v[64:65]
	v_lshl_add_u64 v[66:67], s[6:7], 0, v[128:129]
	v_lshl_add_u64 v[66:67], v[100:101], 1, v[66:67]
	flat_load_dwordx4 v[140:143], v[64:65]
	flat_load_dwordx4 v[132:135], v[66:67]
	flat_load_dwordx4 v[136:139], v[98:99] offset:384
	flat_load_dwordx4 v[128:131], v[102:103] offset:384
	s_and_b64 vcc, exec, s[2:3]
	s_cbranch_vccz .LBB0_834
	ds_read_b128 v[64:67], v175 offset:34816
	s_waitcnt lgkmcnt(0)
	v_mfma_f32_32x32x16_bf16 v[48:63], v[64:67], v[84:87], v[48:63]
	ds_read_b128 v[64:67], v175 offset:34848
	s_waitcnt lgkmcnt(0)
	v_mfma_f32_32x32x16_bf16 v[48:63], v[64:67], v[92:95], v[48:63]
	ds_read_b128 v[64:67], v175 offset:34880
	s_waitcnt lgkmcnt(0)
	v_mfma_f32_32x32x16_bf16 v[48:63], v[64:67], v[80:83], v[48:63]
	ds_read_b128 v[64:67], v175 offset:34912
	s_waitcnt lgkmcnt(0)
	v_mfma_f32_32x32x16_bf16 v[48:63], v[64:67], v[88:91], v[48:63]
	ds_read_b128 v[64:67], v175 offset:39424
	s_waitcnt lgkmcnt(0)
	v_mfma_f32_32x32x16_bf16 v[32:47], v[64:67], v[84:87], v[32:47]
	ds_read_b128 v[64:67], v175 offset:39456
	s_waitcnt lgkmcnt(0)
	v_mfma_f32_32x32x16_bf16 v[32:47], v[64:67], v[92:95], v[32:47]
	ds_read_b128 v[64:67], v175 offset:39488
	s_waitcnt lgkmcnt(0)
	v_mfma_f32_32x32x16_bf16 v[32:47], v[64:67], v[80:83], v[32:47]
	ds_read_b128 v[64:67], v175 offset:39520
	s_waitcnt lgkmcnt(0)
	v_mfma_f32_32x32x16_bf16 v[32:47], v[64:67], v[88:91], v[32:47]
	ds_read_b128 v[64:67], v175 offset:44032
	s_waitcnt lgkmcnt(0)
	v_mfma_f32_32x32x16_bf16 v[16:31], v[64:67], v[84:87], v[16:31]
	ds_read_b128 v[64:67], v175 offset:44064
	s_waitcnt lgkmcnt(0)
	v_mfma_f32_32x32x16_bf16 v[16:31], v[64:67], v[92:95], v[16:31]
	ds_read_b128 v[64:67], v175 offset:44096
	s_waitcnt lgkmcnt(0)
	v_mfma_f32_32x32x16_bf16 v[16:31], v[64:67], v[80:83], v[16:31]
	ds_read_b128 v[64:67], v175 offset:44128
	s_waitcnt lgkmcnt(0)
	v_mfma_f32_32x32x16_bf16 v[16:31], v[64:67], v[88:91], v[16:31]
	ds_read_b128 v[64:67], v175 offset:48640
	s_waitcnt lgkmcnt(0)
	v_mfma_f32_32x32x16_bf16 v[0:15], v[64:67], v[84:87], v[0:15]
	ds_read_b128 v[64:67], v175 offset:48672
	s_waitcnt lgkmcnt(0)
	v_mfma_f32_32x32x16_bf16 v[0:15], v[64:67], v[92:95], v[0:15]
	ds_read_b128 v[64:67], v175 offset:48704
	s_waitcnt lgkmcnt(0)
	v_mfma_f32_32x32x16_bf16 v[0:15], v[64:67], v[80:83], v[0:15]
	ds_read_b128 v[64:67], v175 offset:48736
	s_waitcnt lgkmcnt(0)
	v_mfma_f32_32x32x16_bf16 v[0:15], v[64:67], v[88:91], v[0:15]

.LBB0_838:
	s_waitcnt lgkmcnt(0)
	s_barrier
	s_barrier
	s_movk_i32 s5, 0x1000
	s_andn2_b64 vcc, exec, s[2:3]
	s_waitcnt vmcnt(0)
	ds_write_b128 v177, v[140:143] offset:17408
	ds_write2_b64 v178, v[136:137], v[138:139] offset1:2
	ds_write_b128 v180, v[132:135] offset:17408
	ds_write2_b64 v179, v[128:129], v[130:131] offset1:2
	s_cbranch_vccnz .LBB0_840
	ds_read_b128 v[128:131], v175 offset:53248
	s_waitcnt lgkmcnt(0)
	v_mfma_f32_32x32x16_bf16 v[48:63], v[128:131], v[70:73], v[48:63]
	ds_read_b128 v[128:131], v175 offset:53280
	s_waitcnt lgkmcnt(0)
	v_mfma_f32_32x32x16_bf16 v[48:63], v[128:131], v[78:81], v[48:63]
	ds_read_b128 v[128:131], v175 offset:53312
	s_waitcnt lgkmcnt(0)
	v_mfma_f32_32x32x16_bf16 v[48:63], v[128:131], v[66:69], v[48:63]
	ds_read_b128 v[128:131], v175 offset:53344
	s_waitcnt lgkmcnt(0)
	v_mfma_f32_32x32x16_bf16 v[48:63], v[128:131], v[74:77], v[48:63]
	ds_read_b128 v[128:131], v175 offset:57856
	s_waitcnt lgkmcnt(0)
	v_mfma_f32_32x32x16_bf16 v[32:47], v[128:131], v[70:73], v[32:47]
	ds_read_b128 v[128:131], v175 offset:57888
	s_waitcnt lgkmcnt(0)
	v_mfma_f32_32x32x16_bf16 v[32:47], v[128:131], v[78:81], v[32:47]
	ds_read_b128 v[128:131], v175 offset:57920
	s_waitcnt lgkmcnt(0)
	v_mfma_f32_32x32x16_bf16 v[32:47], v[128:131], v[66:69], v[32:47]
	ds_read_b128 v[128:131], v175 offset:57952
	s_waitcnt lgkmcnt(0)
	v_mfma_f32_32x32x16_bf16 v[32:47], v[128:131], v[74:77], v[32:47]
	ds_read_b128 v[128:131], v175 offset:62464
	s_waitcnt lgkmcnt(0)
	v_mfma_f32_32x32x16_bf16 v[16:31], v[128:131], v[70:73], v[16:31]
	ds_read_b128 v[128:131], v175 offset:62496
	s_waitcnt lgkmcnt(0)
	v_mfma_f32_32x32x16_bf16 v[16:31], v[128:131], v[78:81], v[16:31]
	ds_read_b128 v[128:131], v175 offset:62528
	s_waitcnt lgkmcnt(0)
	v_mfma_f32_32x32x16_bf16 v[16:31], v[128:131], v[66:69], v[16:31]
	ds_read_b128 v[128:131], v175 offset:62560
	s_waitcnt lgkmcnt(0)
	v_mfma_f32_32x32x16_bf16 v[16:31], v[128:131], v[74:77], v[16:31]
	ds_read_b128 v[128:131], v152 offset:32256
	s_waitcnt lgkmcnt(0)
	v_mfma_f32_32x32x16_bf16 v[0:15], v[128:131], v[70:73], v[0:15]
	ds_read_b128 v[70:73], v152 offset:32288
	s_waitcnt lgkmcnt(0)
	v_mfma_f32_32x32x16_bf16 v[0:15], v[70:73], v[78:81], v[0:15]
	ds_read_b128 v[70:73], v152 offset:32320
	s_waitcnt lgkmcnt(0)
	v_mfma_f32_32x32x16_bf16 v[0:15], v[70:73], v[66:69], v[0:15]
	ds_read_b128 v[66:69], v152 offset:32352
	s_waitcnt lgkmcnt(0)
	v_mfma_f32_32x32x16_bf16 v[0:15], v[66:69], v[74:77], v[0:15]

.LBB0_844:
	s_waitcnt lgkmcnt(0)
	s_barrier
	s_barrier
	s_and_b64 vcc, exec, s[2:3]
	s_cbranch_vccz .LBB0_846
	ds_read_b128 v[154:157], v152 offset:36864
	s_waitcnt lgkmcnt(0)
	v_mfma_f32_32x32x16_bf16 v[48:63], v[154:157], v[84:87], v[48:63]
	ds_read_b128 v[154:157], v152 offset:36896
	s_waitcnt lgkmcnt(0)
	v_mfma_f32_32x32x16_bf16 v[48:63], v[154:157], v[92:95], v[48:63]
	ds_read_b128 v[154:157], v152 offset:36928
	s_waitcnt lgkmcnt(0)
	v_mfma_f32_32x32x16_bf16 v[48:63], v[154:157], v[80:83], v[48:63]
	ds_read_b128 v[154:157], v152 offset:36960
	s_waitcnt lgkmcnt(0)
	v_mfma_f32_32x32x16_bf16 v[48:63], v[154:157], v[88:91], v[48:63]
	ds_read_b128 v[154:157], v152 offset:41472
	s_waitcnt lgkmcnt(0)
	v_mfma_f32_32x32x16_bf16 v[32:47], v[154:157], v[84:87], v[32:47]
	ds_read_b128 v[154:157], v152 offset:41504
	s_waitcnt lgkmcnt(0)
	v_mfma_f32_32x32x16_bf16 v[32:47], v[154:157], v[92:95], v[32:47]
	ds_read_b128 v[154:157], v152 offset:41536
	s_waitcnt lgkmcnt(0)
	v_mfma_f32_32x32x16_bf16 v[32:47], v[154:157], v[80:83], v[32:47]
	ds_read_b128 v[154:157], v152 offset:41568
	s_waitcnt lgkmcnt(0)
	v_mfma_f32_32x32x16_bf16 v[32:47], v[154:157], v[88:91], v[32:47]
	ds_read_b128 v[154:157], v152 offset:46080
	s_waitcnt lgkmcnt(0)
	v_mfma_f32_32x32x16_bf16 v[16:31], v[154:157], v[84:87], v[16:31]
	ds_read_b128 v[154:157], v152 offset:46112
	s_waitcnt lgkmcnt(0)
	v_mfma_f32_32x32x16_bf16 v[16:31], v[154:157], v[92:95], v[16:31]
	ds_read_b128 v[154:157], v152 offset:46144
	s_waitcnt lgkmcnt(0)
	v_mfma_f32_32x32x16_bf16 v[16:31], v[154:157], v[80:83], v[16:31]
	ds_read_b128 v[154:157], v152 offset:46176
	s_waitcnt lgkmcnt(0)
	v_mfma_f32_32x32x16_bf16 v[16:31], v[154:157], v[88:91], v[16:31]
	ds_read_b128 v[154:157], v152 offset:50688
	s_waitcnt lgkmcnt(0)
	v_mfma_f32_32x32x16_bf16 v[0:15], v[154:157], v[84:87], v[0:15]
	ds_read_b128 v[84:87], v152 offset:50720
	s_waitcnt lgkmcnt(0)
	v_mfma_f32_32x32x16_bf16 v[0:15], v[84:87], v[92:95], v[0:15]
	ds_read_b128 v[84:87], v152 offset:50752
	s_waitcnt lgkmcnt(0)
	v_mfma_f32_32x32x16_bf16 v[0:15], v[84:87], v[80:83], v[0:15]
	ds_read_b128 v[80:83], v152 offset:50784
	s_waitcnt lgkmcnt(0)
	v_mfma_f32_32x32x16_bf16 v[0:15], v[80:83], v[88:91], v[0:15]

.LBB0_850:
	s_waitcnt lgkmcnt(0)
	s_barrier
	s_barrier
	s_and_b64 vcc, exec, s[2:3]
	s_cbranch_vccz .LBB0_852
	ds_read_b128 v[112:115], v175 offset:34816
	s_waitcnt lgkmcnt(0)
	v_mfma_f32_32x32x16_bf16 v[48:63], v[112:115], v[68:71], v[48:63]
	ds_read_b128 v[112:115], v175 offset:34848
	s_waitcnt lgkmcnt(0)
	v_mfma_f32_32x32x16_bf16 v[48:63], v[112:115], v[76:79], v[48:63]
	ds_read_b128 v[112:115], v175 offset:34880
	s_waitcnt lgkmcnt(0)
	v_mfma_f32_32x32x16_bf16 v[48:63], v[112:115], v[64:67], v[48:63]
	ds_read_b128 v[112:115], v175 offset:34912
	s_waitcnt lgkmcnt(0)
	v_mfma_f32_32x32x16_bf16 v[48:63], v[112:115], v[72:75], v[48:63]
	ds_read_b128 v[112:115], v175 offset:39424
	s_waitcnt lgkmcnt(0)
	v_mfma_f32_32x32x16_bf16 v[32:47], v[112:115], v[68:71], v[32:47]
	ds_read_b128 v[112:115], v175 offset:39456
	s_waitcnt lgkmcnt(0)
	v_mfma_f32_32x32x16_bf16 v[32:47], v[112:115], v[76:79], v[32:47]
	ds_read_b128 v[112:115], v175 offset:39488
	s_waitcnt lgkmcnt(0)
	v_mfma_f32_32x32x16_bf16 v[32:47], v[112:115], v[64:67], v[32:47]
	ds_read_b128 v[112:115], v175 offset:39520
	s_waitcnt lgkmcnt(0)
	v_mfma_f32_32x32x16_bf16 v[32:47], v[112:115], v[72:75], v[32:47]
	ds_read_b128 v[112:115], v175 offset:44032
	s_waitcnt lgkmcnt(0)
	v_mfma_f32_32x32x16_bf16 v[16:31], v[112:115], v[68:71], v[16:31]
	ds_read_b128 v[112:115], v175 offset:44064
	s_waitcnt lgkmcnt(0)
	v_mfma_f32_32x32x16_bf16 v[16:31], v[112:115], v[76:79], v[16:31]
	ds_read_b128 v[112:115], v175 offset:44096
	s_waitcnt lgkmcnt(0)
	v_mfma_f32_32x32x16_bf16 v[16:31], v[112:115], v[64:67], v[16:31]
	ds_read_b128 v[112:115], v175 offset:44128
	s_waitcnt lgkmcnt(0)
	v_mfma_f32_32x32x16_bf16 v[16:31], v[112:115], v[72:75], v[16:31]
	ds_read_b128 v[112:115], v175 offset:48640
	s_waitcnt lgkmcnt(0)
	v_mfma_f32_32x32x16_bf16 v[0:15], v[112:115], v[68:71], v[0:15]
	ds_read_b128 v[68:71], v175 offset:48672
	s_waitcnt lgkmcnt(0)
	v_mfma_f32_32x32x16_bf16 v[0:15], v[68:71], v[76:79], v[0:15]
	ds_read_b128 v[68:71], v175 offset:48704
	s_waitcnt lgkmcnt(0)
	v_mfma_f32_32x32x16_bf16 v[0:15], v[68:71], v[64:67], v[0:15]
	ds_read_b128 v[64:67], v175 offset:48736
	s_waitcnt lgkmcnt(0)
	v_mfma_f32_32x32x16_bf16 v[0:15], v[64:67], v[72:75], v[0:15]
.LBB0_852:
	v_pk_add_f32 v[64:65], v[80:81], 0 op_sel_hi:[1,0]
	v_pk_add_f32 v[66:67], v[96:97], 0 op_sel_hi:[1,0]
	v_pk_add_f32 v[64:65], v[82:83], v[64:65]
	v_pk_add_f32 v[66:67], v[98:99], v[66:67]
	v_pk_add_f32 v[64:65], v[84:85], v[64:65]
	v_pk_add_f32 v[66:67], v[100:101], v[66:67]
	v_pk_add_f32 v[64:65], v[86:87], v[64:65]
	v_pk_add_f32 v[66:67], v[102:103], v[66:67]
	v_pk_add_f32 v[64:65], v[88:89], v[64:65]
	v_pk_add_f32 v[66:67], v[104:105], v[66:67]
	v_pk_add_f32 v[64:65], v[90:91], v[64:65]
	v_pk_add_f32 v[66:67], v[106:107], v[66:67]
	v_pk_add_f32 v[64:65], v[92:93], v[64:65]
	v_pk_add_f32 v[66:67], v[108:109], v[66:67]
	v_pk_add_f32 v[64:65], v[94:95], v[64:65]
	v_pk_add_f32 v[66:67], v[110:111], v[66:67]
	s_cmp_lg_u32 s19, 1
	v_pk_add_f32 v[64:65], v[66:67], v[64:65]
	s_nop 0
	v_add_f32_e32 v64, v64, v65
	v_add_f32_e32 v65, v128, v64
	ds_bpermute_b32 v66, v218, v65
	v_and_b32_e32 v64, 63, v172
	s_barrier
	s_barrier
	s_waitcnt lgkmcnt(0)
	v_add_f32_e32 v65, v65, v66
	v_rcp_f32_e32 v72, v65
	s_cbranch_scc1 .LBB0_854
	s_lshl_b32 s2, s18, 14
	s_add_i32 s2, s2, 0
	v_mul_f32_e32 v65, v48, v72
	v_lshl_add_u32 v66, v64, 2, s2
	v_mul_f32_e32 v67, v49, v72
	ds_write2st64_b32 v66, v65, v67 offset1:1
	v_mul_f32_e32 v65, v50, v72
	v_mul_f32_e32 v67, v51, v72
	ds_write2st64_b32 v66, v65, v67 offset0:2 offset1:3
	v_mul_f32_e32 v65, v52, v72
	v_mul_f32_e32 v67, v53, v72
	ds_write2st64_b32 v66, v65, v67 offset0:4 offset1:5
	v_mul_f32_e32 v65, v54, v72
	v_mul_f32_e32 v67, v55, v72
	ds_write2st64_b32 v66, v65, v67 offset0:6 offset1:7
	v_mul_f32_e32 v65, v56, v72
	v_mul_f32_e32 v67, v57, v72
	ds_write2st64_b32 v66, v65, v67 offset0:8 offset1:9
	v_mul_f32_e32 v65, v58, v72
	v_mul_f32_e32 v67, v59, v72
	ds_write2st64_b32 v66, v65, v67 offset0:10 offset1:11
	v_mul_f32_e32 v65, v60, v72
	v_mul_f32_e32 v67, v61, v72
	ds_write2st64_b32 v66, v65, v67 offset0:12 offset1:13
	v_mul_f32_e32 v65, v62, v72
	v_mul_f32_e32 v67, v63, v72
	ds_write2st64_b32 v66, v65, v67 offset0:14 offset1:15
	v_mul_f32_e32 v65, v32, v72
	v_mul_f32_e32 v67, v33, v72
	ds_write2st64_b32 v66, v65, v67 offset0:16 offset1:17
	v_mul_f32_e32 v65, v34, v72
	v_mul_f32_e32 v67, v35, v72
	ds_write2st64_b32 v66, v65, v67 offset0:18 offset1:19
	v_mul_f32_e32 v65, v36, v72
	v_mul_f32_e32 v67, v37, v72
	ds_write2st64_b32 v66, v65, v67 offset0:20 offset1:21
	v_mul_f32_e32 v65, v38, v72
	v_mul_f32_e32 v67, v39, v72
	ds_write2st64_b32 v66, v65, v67 offset0:22 offset1:23
	v_mul_f32_e32 v65, v40, v72
	v_mul_f32_e32 v67, v41, v72
	ds_write2st64_b32 v66, v65, v67 offset0:24 offset1:25
	v_mul_f32_e32 v65, v42, v72
	v_mul_f32_e32 v67, v43, v72
	ds_write2st64_b32 v66, v65, v67 offset0:26 offset1:27
	v_mul_f32_e32 v65, v44, v72
	v_mul_f32_e32 v67, v45, v72
	ds_write2st64_b32 v66, v65, v67 offset0:28 offset1:29
	v_mul_f32_e32 v65, v46, v72
	v_mul_f32_e32 v67, v47, v72
	ds_write2st64_b32 v66, v65, v67 offset0:30 offset1:31
	v_mul_f32_e32 v65, v16, v72
	v_mul_f32_e32 v67, v17, v72
	ds_write2st64_b32 v66, v65, v67 offset0:32 offset1:33
	v_mul_f32_e32 v65, v18, v72
	v_mul_f32_e32 v67, v19, v72
	ds_write2st64_b32 v66, v65, v67 offset0:34 offset1:35
	v_mul_f32_e32 v65, v20, v72
	v_mul_f32_e32 v67, v21, v72
	ds_write2st64_b32 v66, v65, v67 offset0:36 offset1:37
	v_mul_f32_e32 v65, v22, v72
	v_mul_f32_e32 v67, v23, v72
	ds_write2st64_b32 v66, v65, v67 offset0:38 offset1:39
	v_mul_f32_e32 v65, v24, v72
	v_mul_f32_e32 v67, v25, v72
	ds_write2st64_b32 v66, v65, v67 offset0:40 offset1:41
	v_mul_f32_e32 v65, v26, v72
	v_mul_f32_e32 v67, v27, v72
	ds_write2st64_b32 v66, v65, v67 offset0:42 offset1:43
	v_mul_f32_e32 v65, v28, v72
	v_mul_f32_e32 v67, v29, v72
	ds_write2st64_b32 v66, v65, v67 offset0:44 offset1:45
	v_mul_f32_e32 v65, v30, v72
	v_mul_f32_e32 v67, v31, v72
	ds_write2st64_b32 v66, v65, v67 offset0:46 offset1:47
	v_mul_f32_e32 v65, v0, v72
	v_mul_f32_e32 v67, v1, v72
	ds_write2st64_b32 v66, v65, v67 offset0:48 offset1:49
	v_mul_f32_e32 v65, v2, v72
	v_mul_f32_e32 v67, v3, v72
	ds_write2st64_b32 v66, v65, v67 offset0:50 offset1:51
	v_mul_f32_e32 v65, v4, v72
	v_mul_f32_e32 v67, v5, v72
	ds_write2st64_b32 v66, v65, v67 offset0:52 offset1:53
	v_mul_f32_e32 v65, v6, v72
	v_mul_f32_e32 v67, v7, v72
	ds_write2st64_b32 v66, v65, v67 offset0:54 offset1:55
	v_mul_f32_e32 v65, v8, v72
	v_mul_f32_e32 v67, v9, v72
	ds_write2st64_b32 v66, v65, v67 offset0:56 offset1:57
	v_mul_f32_e32 v65, v10, v72
	v_mul_f32_e32 v67, v11, v72
	ds_write2st64_b32 v66, v65, v67 offset0:58 offset1:59
	v_mul_f32_e32 v65, v12, v72
	v_mul_f32_e32 v67, v13, v72
	ds_write2st64_b32 v66, v65, v67 offset0:60 offset1:61
	v_mul_f32_e32 v65, v14, v72
	v_mul_f32_e32 v67, v15, v72
	ds_write2st64_b32 v66, v65, v67 offset0:62 offset1:63
.LBB0_854:
	s_cmpk_gt_u32 s10, 0xff
	s_waitcnt lgkmcnt(0)
	s_barrier
	s_barrier
	s_cbranch_scc1 .LBB0_829
	s_lshl_b32 s3, s10, 8
	v_lshl_add_u32 v68, v64, 2, 0
	s_and_b32 s4, s3, 0xc000
	v_add_u32_e32 v69, s4, v68
	ds_read2st64_b32 v[96:97], v69 offset1:1
	ds_read2st64_b32 v[98:99], v69 offset0:2 offset1:3
	ds_read2st64_b32 v[104:105], v69 offset0:4 offset1:5
	ds_read2st64_b32 v[108:109], v69 offset0:6 offset1:7
	ds_read2st64_b32 v[112:113], v69 offset0:8 offset1:9
	ds_read2st64_b32 v[114:115], v69 offset0:10 offset1:11
	ds_read2st64_b32 v[120:121], v69 offset0:12 offset1:13
	ds_read2st64_b32 v[124:125], v69 offset0:14 offset1:15
	ds_read2st64_b32 v[126:127], v69 offset0:16 offset1:17
	ds_read2st64_b32 v[122:123], v69 offset0:18 offset1:19
	ds_read2st64_b32 v[128:129], v69 offset0:20 offset1:21
	ds_read2st64_b32 v[134:135], v69 offset0:22 offset1:23
	ds_read2st64_b32 v[130:131], v69 offset0:24 offset1:25
	ds_read2st64_b32 v[138:139], v69 offset0:26 offset1:27
	ds_read2st64_b32 v[142:143], v69 offset0:28 offset1:29
	ds_read2st64_b32 v[166:167], v69 offset0:30 offset1:31
	ds_read2st64_b32 v[136:137], v69 offset0:32 offset1:33
	ds_read2st64_b32 v[148:149], v69 offset0:34 offset1:35
	ds_read2st64_b32 v[150:151], v69 offset0:36 offset1:37
	ds_read2st64_b32 v[152:153], v69 offset0:38 offset1:39
	ds_read2st64_b32 v[102:103], v69 offset0:40 offset1:41
	ds_read2st64_b32 v[106:107], v69 offset0:42 offset1:43
	ds_read2st64_b32 v[90:91], v69 offset0:44 offset1:45
	ds_read2st64_b32 v[92:93], v69 offset0:46 offset1:47
	ds_read2st64_b32 v[86:87], v69 offset0:48 offset1:49
	ds_read2st64_b32 v[88:89], v69 offset0:50 offset1:51
	ds_read2st64_b32 v[82:83], v69 offset0:52 offset1:53
	ds_read2st64_b32 v[84:85], v69 offset0:54 offset1:55
	ds_read2st64_b32 v[78:79], v69 offset0:56 offset1:57
	ds_read2st64_b32 v[80:81], v69 offset0:58 offset1:59
	ds_read2st64_b32 v[64:65], v69 offset0:60 offset1:61
	s_or_b32 s3, s3, 0x3f00
	s_lshl_b32 s2, s17, 7
	s_movk_i32 s4, 0x1400
	s_lshl_b32 s40, s2, 1
	s_waitcnt lgkmcnt(0)
	v_pk_mul_f32 v[64:65], v[144:145], v[64:65]
	v_pk_mul_f32 v[96:97], v[144:145], v[96:97]
	v_pk_fma_f32 v[66:67], v[12:13], v[72:73], v[64:65] op_sel_hi:[1,0,1] neg_lo:[0,0,1] neg_hi:[0,0,1]
	v_add_u32_e32 v13, s3, v68
	ds_read_b32 v12, v69 offset:15872
	ds_read_b32 v13, v13
	v_pk_mul_f32 v[98:99], v[144:145], v[98:99]
	v_pk_mul_f32 v[104:105], v[144:145], v[104:105]
	v_pk_mul_f32 v[108:109], v[144:145], v[108:109]
	v_pk_mul_f32 v[112:113], v[144:145], v[112:113]
	s_waitcnt lgkmcnt(0)
	v_pk_mul_f32 v[12:13], v[144:145], v[12:13]
	v_pk_mul_f32 v[114:115], v[144:145], v[114:115]
	v_pk_fma_f32 v[64:65], v[14:15], v[72:73], v[12:13] op_sel_hi:[1,0,1] neg_lo:[0,0,1] neg_hi:[0,0,1]
	v_mov_b64_e32 v[14:15], s[14:15]
	v_mad_u64_u32 v[14:15], s[2:3], v174, s4, v[14:15]
	v_mov_b32_e32 v68, v15
	v_mad_u64_u32 v[68:69], s[2:3], v173, s4, v[68:69]
	v_mov_b32_e32 v15, v68
	v_lshrrev_b32_e32 v68, 3, v172
	v_and_b32_e32 v73, 4, v68
	v_lshl_add_u64 v[12:13], v[146:147], 0, s[40:41]
	v_lshlrev_b32_e32 v192, 1, v73
	v_lshl_add_u64 v[12:13], v[12:13], 0, v[192:193]
	s_mov_b64 s[2:3], 0x1000
	v_lshl_add_u64 v[68:69], v[12:13], 0, s[2:3]
	v_add_co_u32_e32 v12, vcc, s5, v12
	v_pk_fma_f32 v[96:97], v[48:49], v[72:73], v[96:97] op_sel_hi:[1,0,1] neg_lo:[0,0,1] neg_hi:[0,0,1]
	s_nop 0
	v_addc_co_u32_e32 v13, vcc, 0, v13, vcc
	flat_load_dwordx2 v[100:101], v[12:13]
	flat_load_dwordx2 v[162:163], v[68:69] offset:16
	flat_load_dwordx2 v[140:141], v[68:69] offset:32
	flat_load_dwordx2 v[132:133], v[68:69] offset:48
	flat_load_dwordx2 v[180:181], v[68:69] offset:64
	flat_load_dwordx2 v[186:187], v[68:69] offset:80
	flat_load_dwordx2 v[184:185], v[68:69] offset:96
	flat_load_dwordx2 v[178:179], v[68:69] offset:112
	flat_load_dwordx2 v[146:147], v[68:69] offset:128
	flat_load_dwordx2 v[168:169], v[68:69] offset:144
	flat_load_dwordx2 v[160:161], v[68:69] offset:160
	flat_load_dwordx2 v[154:155], v[68:69] offset:176
	flat_load_dwordx2 v[118:119], v[68:69] offset:192
	flat_load_dwordx2 v[94:95], v[68:69] offset:208
	flat_load_dwordx2 v[70:71], v[68:69] offset:224
	s_nop 0
	flat_load_dwordx2 v[68:69], v[68:69] offset:240
	v_lshlrev_b32_e32 v205, 2, v73
	v_pk_fma_f32 v[50:51], v[50:51], v[72:73], v[98:99] op_sel_hi:[1,0,1] neg_lo:[0,0,1] neg_hi:[0,0,1]
	v_pk_mul_f32 v[120:121], v[144:145], v[120:121]
	v_pk_mul_f32 v[124:125], v[144:145], v[124:125]
	v_pk_mul_f32 v[122:123], v[144:145], v[122:123]
	v_pk_mul_f32 v[80:81], v[144:145], v[80:81]
	v_pk_mul_f32 v[78:79], v[144:145], v[78:79]
	v_pk_mul_f32 v[116:117], v[96:97], v[96:97]
	v_lshl_add_u64 v[156:157], v[14:15], 0, s[40:41]
	global_load_dwordx4 v[12:15], v205, s[0:1]
	global_load_dwordx4 v[240:243], v205, s[0:1] offset:32
	global_load_dwordx4 v[244:247], v205, s[0:1] offset:64
	global_load_dwordx4 v[248:251], v205, s[0:1] offset:96
	v_pk_mul_f32 v[110:111], v[50:51], v[50:51]
	v_pk_mul_f32 v[74:75], v[66:67], v[66:67]
	v_pk_mul_f32 v[76:77], v[64:65], v[64:65]
	s_mov_b32 s2, 0x800000
	s_waitcnt vmcnt(0) lgkmcnt(0)
	v_lshlrev_b32_e32 v48, 16, v100
	v_mul_f32_e32 v73, 0xbfb8aa3b, v48
	v_exp_f32_e32 v73, v73
	v_and_b32_e32 v49, 0xffff0000, v100
	v_add_f32_e32 v73, 1.0, v73
	v_rcp_f32_e32 v98, v73
	v_mul_f32_e32 v73, 0xbfb8aa3b, v49
	v_exp_f32_e32 v73, v73
	s_nop 0
	v_add_f32_e32 v73, 1.0, v73
	v_rcp_f32_e32 v99, v73
	s_nop 0
	v_pk_mul_f32 v[98:99], v[98:99], v[48:49]
	v_lshlrev_b32_e32 v48, 16, v101
	v_mul_f32_e32 v73, 0xbfb8aa3b, v48
	v_exp_f32_e32 v73, v73
	v_and_b32_e32 v49, 0xffff0000, v101
	v_add_f32_e32 v73, 1.0, v73
	v_rcp_f32_e32 v100, v73
	v_mul_f32_e32 v73, 0xbfb8aa3b, v49
	v_exp_f32_e32 v73, v73
	s_nop 0
	v_add_f32_e32 v73, 1.0, v73
	v_pk_fma_f32 v[52:53], v[52:53], v[72:73], v[104:105] op_sel_hi:[1,0,1] neg_lo:[0,0,1] neg_hi:[0,0,1]
	v_lshlrev_b32_e32 v104, 16, v162
	v_rcp_f32_e32 v101, v73
	v_pk_fma_f32 v[54:55], v[54:55], v[72:73], v[108:109] op_sel_hi:[1,0,1] neg_lo:[0,0,1] neg_hi:[0,0,1]
	v_mul_f32_e32 v73, 0xbfb8aa3b, v104
	v_exp_f32_e32 v73, v73
	v_and_b32_e32 v105, 0xffff0000, v162
	v_pk_mul_f32 v[158:159], v[52:53], v[52:53]
	v_pk_mul_f32 v[100:101], v[100:101], v[48:49]
	v_add_f32_e32 v73, 1.0, v73
	v_rcp_f32_e32 v108, v73
	v_mul_f32_e32 v73, 0xbfb8aa3b, v105
	v_exp_f32_e32 v73, v73
	v_lshl_add_u64 v[48:49], v[156:157], 0, v[192:193]
	v_pk_mul_f32 v[156:157], v[54:55], v[54:55]
	v_add_f32_e32 v73, 1.0, v73
	v_rcp_f32_e32 v109, v73
	s_nop 0
	v_pk_mul_f32 v[104:105], v[108:109], v[104:105]
	v_lshlrev_b32_e32 v108, 16, v163
	v_mul_f32_e32 v73, 0xbfb8aa3b, v108
	v_exp_f32_e32 v73, v73
	v_and_b32_e32 v109, 0xffff0000, v163
	v_add_f32_e32 v73, 1.0, v73
	v_rcp_f32_e32 v162, v73
	v_mul_f32_e32 v73, 0xbfb8aa3b, v109
	v_exp_f32_e32 v73, v73
	s_nop 0
	v_add_f32_e32 v73, 1.0, v73
	v_pk_fma_f32 v[56:57], v[56:57], v[72:73], v[112:113] op_sel_hi:[1,0,1] neg_lo:[0,0,1] neg_hi:[0,0,1]
	v_lshlrev_b32_e32 v112, 16, v140
	v_rcp_f32_e32 v163, v73
	v_pk_fma_f32 v[58:59], v[58:59], v[72:73], v[114:115] op_sel_hi:[1,0,1] neg_lo:[0,0,1] neg_hi:[0,0,1]
	v_mul_f32_e32 v73, 0xbfb8aa3b, v112
	v_exp_f32_e32 v73, v73
	v_and_b32_e32 v113, 0xffff0000, v140
	v_pk_mul_f32 v[164:165], v[56:57], v[56:57]
	v_pk_mul_f32 v[108:109], v[162:163], v[108:109]
	v_add_f32_e32 v73, 1.0, v73
	v_rcp_f32_e32 v114, v73
	v_mul_f32_e32 v73, 0xbfb8aa3b, v113
	v_exp_f32_e32 v73, v73
	v_pk_mul_f32 v[162:163], v[58:59], v[58:59]
	v_add_f32_e32 v73, 1.0, v73
	v_rcp_f32_e32 v115, v73
	s_nop 0
	v_pk_mul_f32 v[112:113], v[114:115], v[112:113]
	v_lshlrev_b32_e32 v114, 16, v141
	v_mul_f32_e32 v73, 0xbfb8aa3b, v114
	v_exp_f32_e32 v73, v73
	v_and_b32_e32 v115, 0xffff0000, v141
	v_add_f32_e32 v73, 1.0, v73
	v_rcp_f32_e32 v140, v73
	v_mul_f32_e32 v73, 0xbfb8aa3b, v115
	v_exp_f32_e32 v73, v73
	s_nop 0
	v_add_f32_e32 v73, 1.0, v73
	v_pk_fma_f32 v[60:61], v[60:61], v[72:73], v[120:121] op_sel_hi:[1,0,1] neg_lo:[0,0,1] neg_hi:[0,0,1]
	v_lshlrev_b32_e32 v120, 16, v132
	v_rcp_f32_e32 v141, v73
	v_pk_fma_f32 v[62:63], v[62:63], v[72:73], v[124:125] op_sel_hi:[1,0,1] neg_lo:[0,0,1] neg_hi:[0,0,1]
	v_mul_f32_e32 v73, 0xbfb8aa3b, v120
	v_exp_f32_e32 v73, v73
	v_and_b32_e32 v121, 0xffff0000, v132
	v_pk_mul_f32 v[114:115], v[140:141], v[114:115]
	v_pk_mul_f32 v[172:173], v[60:61], v[60:61]
	v_add_f32_e32 v73, 1.0, v73
	v_rcp_f32_e32 v124, v73
	v_mul_f32_e32 v73, 0xbfb8aa3b, v121
	v_exp_f32_e32 v73, v73
	v_pk_mul_f32 v[170:171], v[62:63], v[62:63]
	v_add_f32_e32 v73, 1.0, v73
	v_rcp_f32_e32 v125, v73
	s_nop 0
	v_pk_mul_f32 v[120:121], v[124:125], v[120:121]
	v_lshlrev_b32_e32 v124, 16, v133
	v_mul_f32_e32 v73, 0xbfb8aa3b, v124
	v_exp_f32_e32 v73, v73
	v_and_b32_e32 v125, 0xffff0000, v133
	v_add_f32_e32 v73, 1.0, v73
	v_rcp_f32_e32 v132, v73
	v_mul_f32_e32 v73, 0xbfb8aa3b, v125
	v_exp_f32_e32 v73, v73
	s_nop 0
	v_add_f32_e32 v73, 1.0, v73
	v_rcp_f32_e32 v133, v73
	v_pk_fma_f32 v[122:123], v[34:35], v[72:73], v[122:123] op_sel_hi:[1,0,1] neg_lo:[0,0,1] neg_hi:[0,0,1]
	v_pk_mul_f32 v[34:35], v[144:145], v[126:127]
	v_pk_mul_f32 v[174:175], v[122:123], v[122:123]
	v_pk_mul_f32 v[124:125], v[132:133], v[124:125]
	v_pk_fma_f32 v[132:133], v[32:33], v[72:73], v[34:35] op_sel_hi:[1,0,1] neg_lo:[0,0,1] neg_hi:[0,0,1]
	v_lshlrev_b32_e32 v32, 16, v180
	v_and_b32_e32 v33, 0xffff0000, v180
	v_mul_f32_e32 v34, 0xbfb8aa3b, v32
	v_mul_f32_e32 v35, 0xbfb8aa3b, v33
	v_exp_f32_e32 v34, v34
	v_exp_f32_e32 v35, v35
	v_pk_mul_f32 v[176:177], v[132:133], v[132:133]
	v_add_f32_e32 v34, 1.0, v34
	v_add_f32_e32 v35, 1.0, v35
	v_rcp_f32_e32 v34, v34
	v_rcp_f32_e32 v35, v35
	s_nop 0
	v_pk_mul_f32 v[140:141], v[34:35], v[32:33]
	v_lshlrev_b32_e32 v32, 16, v181
	v_and_b32_e32 v33, 0xffff0000, v181
	v_mul_f32_e32 v34, 0xbfb8aa3b, v32
	v_mul_f32_e32 v35, 0xbfb8aa3b, v33
	v_exp_f32_e32 v34, v34
	v_exp_f32_e32 v35, v35
	v_add_f32_e32 v34, 1.0, v34
	v_add_f32_e32 v35, 1.0, v35
	v_rcp_f32_e32 v34, v34
	v_rcp_f32_e32 v35, v35
	s_nop 0
	v_pk_mul_f32 v[126:127], v[34:35], v[32:33]
	v_pk_mul_f32 v[34:35], v[144:145], v[128:129]
	v_pk_mul_f32 v[32:33], v[144:145], v[134:135]
	v_pk_fma_f32 v[128:129], v[36:37], v[72:73], v[34:35] op_sel_hi:[1,0,1] neg_lo:[0,0,1] neg_hi:[0,0,1]
	v_lshlrev_b32_e32 v34, 16, v186
	v_and_b32_e32 v35, 0xffff0000, v186
	v_mul_f32_e32 v36, 0xbfb8aa3b, v34
	v_mul_f32_e32 v37, 0xbfb8aa3b, v35
	v_exp_f32_e32 v36, v36
	v_exp_f32_e32 v37, v37
	v_pk_fma_f32 v[32:33], v[38:39], v[72:73], v[32:33] op_sel_hi:[1,0,1] neg_lo:[0,0,1] neg_hi:[0,0,1]
	v_pk_mul_f32 v[182:183], v[128:129], v[128:129]
	v_add_f32_e32 v36, 1.0, v36
	v_add_f32_e32 v37, 1.0, v37
	v_rcp_f32_e32 v36, v36
	v_rcp_f32_e32 v37, v37
	v_pk_mul_f32 v[180:181], v[32:33], v[32:33]
	v_pk_mul_f32 v[134:135], v[36:37], v[34:35]
	v_lshlrev_b32_e32 v34, 16, v187
	v_and_b32_e32 v35, 0xffff0000, v187
	v_mul_f32_e32 v36, 0xbfb8aa3b, v34
	v_mul_f32_e32 v37, 0xbfb8aa3b, v35
	v_exp_f32_e32 v36, v36
	v_exp_f32_e32 v37, v37
	v_add_f32_e32 v36, 1.0, v36
	v_add_f32_e32 v37, 1.0, v37
	v_rcp_f32_e32 v36, v36
	v_rcp_f32_e32 v37, v37
	s_nop 0
	v_pk_mul_f32 v[38:39], v[36:37], v[34:35]
	v_pk_mul_f32 v[36:37], v[144:145], v[130:131]
	v_pk_mul_f32 v[34:35], v[144:145], v[138:139]
	v_pk_fma_f32 v[130:131], v[40:41], v[72:73], v[36:37] op_sel_hi:[1,0,1] neg_lo:[0,0,1] neg_hi:[0,0,1]
	v_lshlrev_b32_e32 v36, 16, v184
	v_and_b32_e32 v37, 0xffff0000, v184
	v_mul_f32_e32 v40, 0xbfb8aa3b, v36
	v_mul_f32_e32 v41, 0xbfb8aa3b, v37
	v_exp_f32_e32 v40, v40
	v_exp_f32_e32 v41, v41
	v_pk_fma_f32 v[34:35], v[42:43], v[72:73], v[34:35] op_sel_hi:[1,0,1] neg_lo:[0,0,1] neg_hi:[0,0,1]
	v_pk_mul_f32 v[42:43], v[144:145], v[142:143]
	v_add_f32_e32 v40, 1.0, v40
	v_add_f32_e32 v41, 1.0, v41
	v_rcp_f32_e32 v40, v40
	v_rcp_f32_e32 v41, v41
	v_pk_mul_f32 v[188:189], v[130:131], v[130:131]
	v_pk_mul_f32 v[186:187], v[34:35], v[34:35]
	v_pk_mul_f32 v[138:139], v[40:41], v[36:37]
	v_lshlrev_b32_e32 v36, 16, v185
	v_and_b32_e32 v37, 0xffff0000, v185
	v_mul_f32_e32 v40, 0xbfb8aa3b, v36
	v_mul_f32_e32 v41, 0xbfb8aa3b, v37
	v_exp_f32_e32 v40, v40
	v_exp_f32_e32 v41, v41
	v_add_f32_e32 v40, 1.0, v40
	v_add_f32_e32 v41, 1.0, v41
	v_rcp_f32_e32 v40, v40
	v_rcp_f32_e32 v41, v41
	s_nop 0
	v_pk_mul_f32 v[40:41], v[40:41], v[36:37]
	v_pk_mul_f32 v[36:37], v[144:145], v[166:167]
	s_nop 0
	v_pk_fma_f32 v[36:37], v[46:47], v[72:73], v[36:37] op_sel_hi:[1,0,1] neg_lo:[0,0,1] neg_hi:[0,0,1]
	v_pk_fma_f32 v[46:47], v[44:45], v[72:73], v[42:43] op_sel_hi:[1,0,1] neg_lo:[0,0,1] neg_hi:[0,0,1]
	v_lshlrev_b32_e32 v42, 16, v178
	v_and_b32_e32 v43, 0xffff0000, v178
	v_mul_f32_e32 v44, 0xbfb8aa3b, v42
	v_mul_f32_e32 v45, 0xbfb8aa3b, v43
	v_exp_f32_e32 v44, v44
	v_exp_f32_e32 v45, v45
	v_pk_mul_f32 v[184:185], v[46:47], v[46:47]
	v_pk_mul_f32 v[166:167], v[36:37], v[36:37]
	v_add_f32_e32 v44, 1.0, v44
	v_add_f32_e32 v45, 1.0, v45
	v_rcp_f32_e32 v44, v44
	v_rcp_f32_e32 v45, v45
	s_nop 0
	v_pk_mul_f32 v[142:143], v[44:45], v[42:43]
	v_lshlrev_b32_e32 v42, 16, v179
	v_and_b32_e32 v43, 0xffff0000, v179
	v_mul_f32_e32 v44, 0xbfb8aa3b, v42
	v_mul_f32_e32 v45, 0xbfb8aa3b, v43
	v_exp_f32_e32 v44, v44
	v_exp_f32_e32 v45, v45
	v_add_f32_e32 v44, 1.0, v44
	v_add_f32_e32 v45, 1.0, v45
	v_rcp_f32_e32 v44, v44
	v_rcp_f32_e32 v45, v45
	s_nop 0
	v_pk_mul_f32 v[42:43], v[44:45], v[42:43]
	v_pk_mul_f32 v[44:45], v[144:145], v[148:149]
	s_nop 0
	v_pk_fma_f32 v[18:19], v[18:19], v[72:73], v[44:45] op_sel_hi:[1,0,1] neg_lo:[0,0,1] neg_hi:[0,0,1]
	v_pk_mul_f32 v[44:45], v[144:145], v[136:137]
	v_pk_mul_f32 v[178:179], v[18:19], v[18:19]
	v_pk_fma_f32 v[136:137], v[16:17], v[72:73], v[44:45] op_sel_hi:[1,0,1] neg_lo:[0,0,1] neg_hi:[0,0,1]
	v_lshlrev_b32_e32 v16, 16, v146
	v_and_b32_e32 v17, 0xffff0000, v146
	v_mul_f32_e32 v44, 0xbfb8aa3b, v16
	v_mul_f32_e32 v45, 0xbfb8aa3b, v17
	v_exp_f32_e32 v44, v44
	v_exp_f32_e32 v45, v45
	v_pk_mul_f32 v[190:191], v[136:137], v[136:137]
	v_add_f32_e32 v44, 1.0, v44
	v_add_f32_e32 v45, 1.0, v45
	v_rcp_f32_e32 v44, v44
	v_rcp_f32_e32 v45, v45
	s_nop 0
	v_pk_mul_f32 v[148:149], v[44:45], v[16:17]
	v_lshlrev_b32_e32 v16, 16, v147
	v_and_b32_e32 v17, 0xffff0000, v147
	v_mul_f32_e32 v44, 0xbfb8aa3b, v16
	v_mul_f32_e32 v45, 0xbfb8aa3b, v17
	v_exp_f32_e32 v44, v44
	v_exp_f32_e32 v45, v45
	v_add_f32_e32 v44, 1.0, v44
	v_add_f32_e32 v45, 1.0, v45
	v_rcp_f32_e32 v44, v44
	v_rcp_f32_e32 v45, v45
	s_nop 0
	v_pk_mul_f32 v[44:45], v[44:45], v[16:17]
	v_pk_mul_f32 v[16:17], v[144:145], v[152:153]
	s_nop 0
	v_pk_fma_f32 v[16:17], v[22:23], v[72:73], v[16:17] op_sel_hi:[1,0,1] neg_lo:[0,0,1] neg_hi:[0,0,1]
	v_pk_mul_f32 v[22:23], v[144:145], v[150:151]
	v_pk_mul_f32 v[152:153], v[16:17], v[16:17]
	v_pk_fma_f32 v[146:147], v[20:21], v[72:73], v[22:23] op_sel_hi:[1,0,1] neg_lo:[0,0,1] neg_hi:[0,0,1]
	v_lshlrev_b32_e32 v20, 16, v168
	v_and_b32_e32 v21, 0xffff0000, v168
	v_mul_f32_e32 v22, 0xbfb8aa3b, v20
	v_mul_f32_e32 v23, 0xbfb8aa3b, v21
	v_exp_f32_e32 v22, v22
	v_exp_f32_e32 v23, v23
	v_pk_mul_f32 v[194:195], v[146:147], v[146:147]
	v_add_f32_e32 v22, 1.0, v22
	v_add_f32_e32 v23, 1.0, v23
	v_rcp_f32_e32 v22, v22
	v_rcp_f32_e32 v23, v23
	s_nop 0
	v_pk_mul_f32 v[150:151], v[22:23], v[20:21]
	v_lshlrev_b32_e32 v20, 16, v169
	v_and_b32_e32 v21, 0xffff0000, v169
	v_mul_f32_e32 v22, 0xbfb8aa3b, v20
	v_mul_f32_e32 v23, 0xbfb8aa3b, v21
	v_exp_f32_e32 v22, v22
	v_exp_f32_e32 v23, v23
	v_add_f32_e32 v22, 1.0, v22
	v_add_f32_e32 v23, 1.0, v23
	v_rcp_f32_e32 v22, v22
	v_rcp_f32_e32 v23, v23
	s_nop 0
	v_pk_mul_f32 v[22:23], v[22:23], v[20:21]
	v_pk_mul_f32 v[20:21], v[144:145], v[106:107]
	s_nop 0
	v_pk_fma_f32 v[20:21], v[26:27], v[72:73], v[20:21] op_sel_hi:[1,0,1] neg_lo:[0,0,1] neg_hi:[0,0,1]
	v_pk_mul_f32 v[26:27], v[144:145], v[102:103]
	v_pk_mul_f32 v[168:169], v[20:21], v[20:21]
	v_pk_fma_f32 v[102:103], v[24:25], v[72:73], v[26:27] op_sel_hi:[1,0,1] neg_lo:[0,0,1] neg_hi:[0,0,1]
	v_lshlrev_b32_e32 v24, 16, v160
	v_and_b32_e32 v25, 0xffff0000, v160
	v_mul_f32_e32 v26, 0xbfb8aa3b, v24
	v_mul_f32_e32 v27, 0xbfb8aa3b, v25
	v_exp_f32_e32 v26, v26
	v_exp_f32_e32 v27, v27
	v_pk_mul_f32 v[196:197], v[102:103], v[102:103]
	v_add_f32_e32 v26, 1.0, v26
	v_add_f32_e32 v27, 1.0, v27
	v_rcp_f32_e32 v26, v26
	v_rcp_f32_e32 v27, v27
	s_nop 0
	v_pk_mul_f32 v[106:107], v[26:27], v[24:25]
	v_lshlrev_b32_e32 v24, 16, v161
	v_and_b32_e32 v25, 0xffff0000, v161
	v_mul_f32_e32 v26, 0xbfb8aa3b, v24
	v_mul_f32_e32 v27, 0xbfb8aa3b, v25
	v_exp_f32_e32 v26, v26
	v_exp_f32_e32 v27, v27
	v_add_f32_e32 v26, 1.0, v26
	v_add_f32_e32 v27, 1.0, v27
	v_rcp_f32_e32 v26, v26
	v_rcp_f32_e32 v27, v27
	s_nop 0
	v_pk_mul_f32 v[26:27], v[26:27], v[24:25]
	v_pk_mul_f32 v[24:25], v[144:145], v[92:93]
	s_nop 0
	v_pk_fma_f32 v[24:25], v[30:31], v[72:73], v[24:25] op_sel_hi:[1,0,1] neg_lo:[0,0,1] neg_hi:[0,0,1]
	v_pk_mul_f32 v[30:31], v[144:145], v[90:91]
	v_pk_mul_f32 v[160:161], v[24:25], v[24:25]
	v_pk_fma_f32 v[90:91], v[28:29], v[72:73], v[30:31] op_sel_hi:[1,0,1] neg_lo:[0,0,1] neg_hi:[0,0,1]
	v_lshlrev_b32_e32 v28, 16, v154
	v_and_b32_e32 v29, 0xffff0000, v154
	v_mul_f32_e32 v30, 0xbfb8aa3b, v28
	v_mul_f32_e32 v31, 0xbfb8aa3b, v29
	v_exp_f32_e32 v30, v30
	v_exp_f32_e32 v31, v31
	v_pk_mul_f32 v[198:199], v[90:91], v[90:91]
	v_add_f32_e32 v30, 1.0, v30
	v_add_f32_e32 v31, 1.0, v31
	v_rcp_f32_e32 v30, v30
	v_rcp_f32_e32 v31, v31
	s_nop 0
	v_pk_mul_f32 v[92:93], v[30:31], v[28:29]
	v_lshlrev_b32_e32 v28, 16, v155
	v_and_b32_e32 v29, 0xffff0000, v155
	v_mul_f32_e32 v30, 0xbfb8aa3b, v28
	v_mul_f32_e32 v31, 0xbfb8aa3b, v29
	v_exp_f32_e32 v30, v30
	v_exp_f32_e32 v31, v31
	v_add_f32_e32 v30, 1.0, v30
	v_add_f32_e32 v31, 1.0, v31
	v_rcp_f32_e32 v30, v30
	v_rcp_f32_e32 v31, v31
	s_nop 0
	v_pk_mul_f32 v[28:29], v[30:31], v[28:29]
	v_pk_mul_f32 v[30:31], v[144:145], v[88:89]
	s_nop 0
	v_pk_fma_f32 v[2:3], v[2:3], v[72:73], v[30:31] op_sel_hi:[1,0,1] neg_lo:[0,0,1] neg_hi:[0,0,1]
	v_pk_mul_f32 v[30:31], v[144:145], v[86:87]
	v_pk_mul_f32 v[154:155], v[2:3], v[2:3]
	v_pk_fma_f32 v[86:87], v[0:1], v[72:73], v[30:31] op_sel_hi:[1,0,1] neg_lo:[0,0,1] neg_hi:[0,0,1]
	v_lshlrev_b32_e32 v0, 16, v118
	v_and_b32_e32 v1, 0xffff0000, v118
	v_mul_f32_e32 v30, 0xbfb8aa3b, v0
	v_mul_f32_e32 v31, 0xbfb8aa3b, v1
	v_exp_f32_e32 v30, v30
	v_exp_f32_e32 v31, v31
	v_pk_mul_f32 v[200:201], v[86:87], v[86:87]
	v_add_f32_e32 v30, 1.0, v30
	v_add_f32_e32 v31, 1.0, v31
	v_rcp_f32_e32 v30, v30
	v_rcp_f32_e32 v31, v31
	s_nop 0
	v_pk_mul_f32 v[88:89], v[30:31], v[0:1]
	v_lshlrev_b32_e32 v0, 16, v119
	v_and_b32_e32 v1, 0xffff0000, v119
	v_mul_f32_e32 v30, 0xbfb8aa3b, v0
	v_mul_f32_e32 v31, 0xbfb8aa3b, v1
	v_exp_f32_e32 v30, v30
	v_exp_f32_e32 v31, v31
	v_add_f32_e32 v30, 1.0, v30
	v_add_f32_e32 v31, 1.0, v31
	v_rcp_f32_e32 v30, v30
	v_rcp_f32_e32 v31, v31
	s_nop 0
	v_pk_mul_f32 v[30:31], v[30:31], v[0:1]
	v_pk_mul_f32 v[0:1], v[144:145], v[84:85]
	s_nop 0
	v_pk_fma_f32 v[0:1], v[6:7], v[72:73], v[0:1] op_sel_hi:[1,0,1] neg_lo:[0,0,1] neg_hi:[0,0,1]
	v_pk_mul_f32 v[6:7], v[144:145], v[82:83]
	v_pk_mul_f32 v[84:85], v[0:1], v[0:1]
	v_pk_fma_f32 v[6:7], v[4:5], v[72:73], v[6:7] op_sel_hi:[1,0,1] neg_lo:[0,0,1] neg_hi:[0,0,1]
	v_lshlrev_b32_e32 v4, 16, v94
	v_mul_f32_e32 v73, 0xbfb8aa3b, v4
	v_exp_f32_e32 v73, v73
	v_and_b32_e32 v5, 0xffff0000, v94
	v_pk_mul_f32 v[118:119], v[6:7], v[6:7]
	v_add_f32_e32 v73, 1.0, v73
	v_rcp_f32_e32 v82, v73
	v_mul_f32_e32 v73, 0xbfb8aa3b, v5
	v_exp_f32_e32 v73, v73
	s_nop 0
	v_add_f32_e32 v73, 1.0, v73
	v_rcp_f32_e32 v83, v73
	s_nop 0
	v_pk_mul_f32 v[82:83], v[82:83], v[4:5]
	v_lshlrev_b32_e32 v4, 16, v95
	v_mul_f32_e32 v73, 0xbfb8aa3b, v4
	v_exp_f32_e32 v73, v73
	v_and_b32_e32 v5, 0xffff0000, v95
	v_add_f32_e32 v73, 1.0, v73
	v_rcp_f32_e32 v94, v73
	v_mul_f32_e32 v73, 0xbfb8aa3b, v5
	v_exp_f32_e32 v73, v73
	s_nop 0
	v_add_f32_e32 v73, 1.0, v73
	v_rcp_f32_e32 v95, v73
	v_pk_fma_f32 v[10:11], v[10:11], v[72:73], v[80:81] op_sel_hi:[1,0,1] neg_lo:[0,0,1] neg_hi:[0,0,1]
	v_pk_fma_f32 v[72:73], v[8:9], v[72:73], v[78:79] op_sel_hi:[1,0,1] neg_lo:[0,0,1] neg_hi:[0,0,1]
	v_lshlrev_b32_e32 v78, 16, v70
	v_and_b32_e32 v79, 0xffff0000, v70
	v_mul_f32_e32 v70, 0xbfb8aa3b, v78
	v_exp_f32_e32 v70, v70
	v_pk_mul_f32 v[4:5], v[94:95], v[4:5]
	v_pk_mul_f32 v[8:9], v[72:73], v[72:73]
	v_pk_mul_f32 v[80:81], v[10:11], v[10:11]
	v_add_f32_e32 v70, 1.0, v70
	v_rcp_f32_e32 v94, v70
	v_mul_f32_e32 v70, 0xbfb8aa3b, v79
	v_exp_f32_e32 v70, v70
	s_nop 0
	v_add_f32_e32 v70, 1.0, v70
	v_rcp_f32_e32 v95, v70
	v_add_f32_e32 v70, v116, v117
	v_add_f32_e32 v70, v70, v110
	v_add_f32_e32 v70, v70, v111
	v_add_f32_e32 v70, v70, v158
	v_add_f32_e32 v70, v70, v159
	v_add_f32_e32 v70, v70, v156
	v_add_f32_e32 v70, v70, v157
	v_add_f32_e32 v70, v70, v164
	v_add_f32_e32 v70, v70, v165
	v_add_f32_e32 v70, v70, v162
	v_add_f32_e32 v70, v70, v163
	v_add_f32_e32 v70, v70, v172
	v_add_f32_e32 v70, v70, v173
	v_add_f32_e32 v70, v70, v170
	v_add_f32_e32 v70, v70, v171
	v_add_f32_e32 v70, v70, v176
	v_add_f32_e32 v70, v70, v177
	v_add_f32_e32 v70, v70, v174
	v_add_f32_e32 v70, v70, v175
	v_add_f32_e32 v70, v70, v182
	v_add_f32_e32 v70, v70, v183
	v_add_f32_e32 v70, v70, v180
	v_add_f32_e32 v70, v70, v181
	v_add_f32_e32 v70, v70, v188
	v_add_f32_e32 v70, v70, v189
	v_add_f32_e32 v70, v70, v186
	v_add_f32_e32 v70, v70, v187
	v_add_f32_e32 v70, v70, v184
	v_add_f32_e32 v70, v70, v185
	v_add_f32_e32 v70, v70, v166
	v_add_f32_e32 v70, v70, v167
	v_add_f32_e32 v70, v70, v190
	v_add_f32_e32 v70, v70, v191
	v_add_f32_e32 v70, v70, v178
	v_add_f32_e32 v70, v70, v179
	v_add_f32_e32 v70, v70, v194
	v_add_f32_e32 v70, v70, v195
	v_add_f32_e32 v70, v70, v152
	v_add_f32_e32 v70, v70, v153
	v_add_f32_e32 v70, v70, v196
	v_add_f32_e32 v70, v70, v197
	v_add_f32_e32 v70, v70, v168
	v_add_f32_e32 v70, v70, v169
	v_add_f32_e32 v70, v70, v198
	v_add_f32_e32 v70, v70, v199
	v_add_f32_e32 v70, v70, v160
	v_add_f32_e32 v70, v70, v161
	v_add_f32_e32 v70, v70, v200
	v_add_f32_e32 v70, v70, v201
	v_add_f32_e32 v70, v70, v154
	v_add_f32_e32 v70, v70, v155
	v_add_f32_e32 v70, v70, v118
	v_add_f32_e32 v70, v70, v119
	v_add_f32_e32 v70, v70, v84
	v_add_f32_e32 v70, v70, v85
	v_add_f32_e32 v8, v70, v8
	v_add_f32_e32 v8, v8, v9
	v_add_f32_e32 v8, v8, v80
	v_add_f32_e32 v8, v8, v81
	v_add_f32_e32 v8, v8, v74
	v_add_f32_e32 v8, v8, v75
	v_add_f32_e32 v8, v8, v76
	v_add_f32_e32 v8, v8, v77
	ds_bpermute_b32 v9, v218, v8
	v_pk_mul_f32 v[78:79], v[94:95], v[78:79]
	s_waitcnt lgkmcnt(0)
	v_add_f32_e32 v8, v8, v9
	v_fmamk_f32 v8, v8, 0x3c000000, v207
	v_cmp_gt_f32_e32 vcc, s2, v8
	v_mul_f32_e32 v9, 0x4b800000, v8
	s_nop 0
	v_cndmask_b32_e32 v8, v8, v9, vcc
	v_rsq_f32_e32 v8, v8
	s_nop 0
	v_mul_f32_e32 v9, 0x45800000, v8
	v_cndmask_b32_e32 v8, v8, v9, vcc
	v_mul_f32_e32 v8, v204, v8
	v_pk_mul_f32 v[74:75], v[96:97], v[8:9] op_sel_hi:[1,0]
	v_pk_mul_f32 v[50:51], v[50:51], v[8:9] op_sel_hi:[1,0]
	v_pk_mul_f32 v[12:13], v[74:75], v[12:13]
	v_pk_mul_f32 v[14:15], v[50:51], v[14:15]
	v_pk_mul_f32 v[12:13], v[98:99], v[12:13]
	v_pk_mul_f32 v[14:15], v[100:101], v[14:15]
	v_cvt_pk_bf16_f32 v12, v12, v13
	v_cvt_pk_bf16_f32 v13, v14, v15
	flat_store_dwordx2 v[48:49], v[12:13] offset:1024
	global_load_dwordx4 v[252:255], v205, s[0:1] offset:128
	v_pk_mul_f32 v[50:51], v[52:53], v[8:9] op_sel_hi:[1,0]
	v_pk_mul_f32 v[32:33], v[32:33], v[8:9] op_sel_hi:[1,0]
	v_pk_mul_f32 v[18:19], v[18:19], v[8:9] op_sel_hi:[1,0]
	v_pk_mul_f32 v[16:17], v[16:17], v[8:9] op_sel_hi:[1,0]
	v_pk_mul_f32 v[2:3], v[2:3], v[8:9] op_sel_hi:[1,0]
	v_pk_mul_f32 v[0:1], v[0:1], v[8:9] op_sel_hi:[1,0]
	v_pk_mul_f32 v[10:11], v[10:11], v[8:9] op_sel_hi:[1,0]
	v_pk_mul_f32 v[12:13], v[50:51], v[240:241]
	v_pk_mul_f32 v[50:51], v[54:55], v[8:9] op_sel_hi:[1,0]
	v_pk_mul_f32 v[12:13], v[104:105], v[12:13]
	v_pk_mul_f32 v[14:15], v[50:51], v[242:243]
	v_cvt_pk_bf16_f32 v12, v12, v13
	v_pk_mul_f32 v[14:15], v[108:109], v[14:15]
	v_pk_mul_f32 v[50:51], v[56:57], v[8:9] op_sel_hi:[1,0]
	v_cvt_pk_bf16_f32 v13, v14, v15
	flat_store_dwordx2 v[48:49], v[12:13] offset:1040
	global_load_dwordx4 v[240:243], v205, s[0:1] offset:160
	v_pk_mul_f32 v[12:13], v[50:51], v[244:245]
	v_pk_mul_f32 v[50:51], v[58:59], v[8:9] op_sel_hi:[1,0]
	v_pk_mul_f32 v[12:13], v[112:113], v[12:13]
	v_pk_mul_f32 v[14:15], v[50:51], v[246:247]
	v_cvt_pk_bf16_f32 v12, v12, v13
	v_pk_mul_f32 v[14:15], v[114:115], v[14:15]
	v_pk_mul_f32 v[50:51], v[60:61], v[8:9] op_sel_hi:[1,0]
	v_cvt_pk_bf16_f32 v13, v14, v15
	flat_store_dwordx2 v[48:49], v[12:13] offset:1056
	global_load_dwordx4 v[244:247], v205, s[0:1] offset:192
	v_pk_mul_f32 v[12:13], v[50:51], v[248:249]
	v_pk_mul_f32 v[50:51], v[62:63], v[8:9] op_sel_hi:[1,0]
	v_pk_mul_f32 v[12:13], v[120:121], v[12:13]
	v_pk_mul_f32 v[14:15], v[50:51], v[250:251]
	v_cvt_pk_bf16_f32 v12, v12, v13
	v_pk_mul_f32 v[14:15], v[124:125], v[14:15]
	v_pk_mul_f32 v[50:51], v[132:133], v[8:9] op_sel_hi:[1,0]
	v_cvt_pk_bf16_f32 v13, v14, v15
	flat_store_dwordx2 v[48:49], v[12:13] offset:1072
	global_load_dwordx4 v[248:251], v205, s[0:1] offset:224
	s_waitcnt vmcnt(6)
	v_pk_mul_f32 v[12:13], v[50:51], v[252:253]
	v_pk_mul_f32 v[50:51], v[122:123], v[8:9] op_sel_hi:[1,0]
	v_pk_mul_f32 v[12:13], v[140:141], v[12:13]
	v_pk_mul_f32 v[14:15], v[50:51], v[254:255]
	v_cvt_pk_bf16_f32 v12, v12, v13
	v_pk_mul_f32 v[14:15], v[126:127], v[14:15]
	v_pk_mul_f32 v[50:51], v[128:129], v[8:9] op_sel_hi:[1,0]
	v_cvt_pk_bf16_f32 v13, v14, v15
	flat_store_dwordx2 v[48:49], v[12:13] offset:1088
	global_load_dwordx4 v[252:255], v205, s[0:1] offset:256
	s_waitcnt vmcnt(6)
	v_pk_mul_f32 v[12:13], v[50:51], v[240:241]
	v_pk_mul_f32 v[14:15], v[32:33], v[242:243]
	v_pk_mul_f32 v[12:13], v[134:135], v[12:13]
	v_pk_mul_f32 v[14:15], v[38:39], v[14:15]
	v_cvt_pk_bf16_f32 v12, v12, v13
	v_cvt_pk_bf16_f32 v13, v14, v15
	flat_store_dwordx2 v[48:49], v[12:13] offset:1104
	global_load_dwordx4 v[240:243], v205, s[0:1] offset:288
	v_pk_mul_f32 v[32:33], v[130:131], v[8:9] op_sel_hi:[1,0]
	s_waitcnt vmcnt(6)
	v_pk_mul_f32 v[12:13], v[32:33], v[244:245]
	v_pk_mul_f32 v[32:33], v[34:35], v[8:9] op_sel_hi:[1,0]
	v_pk_mul_f32 v[12:13], v[138:139], v[12:13]
	v_pk_mul_f32 v[14:15], v[32:33], v[246:247]
	v_cvt_pk_bf16_f32 v12, v12, v13
	v_pk_mul_f32 v[14:15], v[40:41], v[14:15]
	v_pk_mul_f32 v[32:33], v[46:47], v[8:9] op_sel_hi:[1,0]
	v_cvt_pk_bf16_f32 v13, v14, v15
	flat_store_dwordx2 v[48:49], v[12:13] offset:1120
	global_load_dwordx4 v[244:247], v205, s[0:1] offset:320
	s_waitcnt vmcnt(6)
	v_pk_mul_f32 v[12:13], v[32:33], v[248:249]
	v_pk_mul_f32 v[32:33], v[36:37], v[8:9] op_sel_hi:[1,0]
	v_pk_mul_f32 v[12:13], v[142:143], v[12:13]
	v_pk_mul_f32 v[14:15], v[32:33], v[250:251]
	v_cvt_pk_bf16_f32 v12, v12, v13
	v_pk_mul_f32 v[14:15], v[42:43], v[14:15]
	v_pk_mul_f32 v[32:33], v[136:137], v[8:9] op_sel_hi:[1,0]
	v_cvt_pk_bf16_f32 v13, v14, v15
	flat_store_dwordx2 v[48:49], v[12:13] offset:1136
	global_load_dwordx4 v[248:251], v205, s[0:1] offset:352
	s_waitcnt vmcnt(6)
	v_pk_mul_f32 v[12:13], v[32:33], v[252:253]
	v_pk_mul_f32 v[14:15], v[18:19], v[254:255]
	v_pk_mul_f32 v[12:13], v[148:149], v[12:13]
	v_pk_mul_f32 v[14:15], v[44:45], v[14:15]
	v_cvt_pk_bf16_f32 v12, v12, v13
	v_cvt_pk_bf16_f32 v13, v14, v15
	flat_store_dwordx2 v[48:49], v[12:13] offset:1152
	global_load_dwordx4 v[252:255], v205, s[0:1] offset:384
	v_pk_mul_f32 v[18:19], v[146:147], v[8:9] op_sel_hi:[1,0]
	s_waitcnt vmcnt(6)
	v_pk_mul_f32 v[14:15], v[16:17], v[242:243]
	v_pk_mul_f32 v[12:13], v[18:19], v[240:241]
	v_pk_mul_f32 v[14:15], v[22:23], v[14:15]
	v_pk_mul_f32 v[12:13], v[150:151], v[12:13]
	v_pk_mul_f32 v[16:17], v[102:103], v[8:9] op_sel_hi:[1,0]
	v_cvt_pk_bf16_f32 v12, v12, v13
	v_cvt_pk_bf16_f32 v13, v14, v15
	flat_store_dwordx2 v[48:49], v[12:13] offset:1168
	global_load_dwordx4 v[240:243], v205, s[0:1] offset:416
	s_waitcnt vmcnt(6)
	v_pk_mul_f32 v[12:13], v[16:17], v[244:245]
	v_pk_mul_f32 v[16:17], v[20:21], v[8:9] op_sel_hi:[1,0]
	v_pk_mul_f32 v[12:13], v[106:107], v[12:13]
	v_pk_mul_f32 v[14:15], v[16:17], v[246:247]
	v_cvt_pk_bf16_f32 v12, v12, v13
	v_pk_mul_f32 v[14:15], v[26:27], v[14:15]
	v_pk_mul_f32 v[16:17], v[90:91], v[8:9] op_sel_hi:[1,0]
	v_cvt_pk_bf16_f32 v13, v14, v15
	flat_store_dwordx2 v[48:49], v[12:13] offset:1184
	global_load_dwordx4 v[244:247], v205, s[0:1] offset:448
	s_waitcnt vmcnt(6)
	v_pk_mul_f32 v[12:13], v[16:17], v[248:249]
	v_pk_mul_f32 v[16:17], v[24:25], v[8:9] op_sel_hi:[1,0]
	v_pk_mul_f32 v[12:13], v[92:93], v[12:13]
	v_pk_mul_f32 v[14:15], v[16:17], v[250:251]
	v_cvt_pk_bf16_f32 v12, v12, v13
	v_pk_mul_f32 v[14:15], v[28:29], v[14:15]
	v_pk_mul_f32 v[16:17], v[86:87], v[8:9] op_sel_hi:[1,0]
	v_cvt_pk_bf16_f32 v13, v14, v15
	flat_store_dwordx2 v[48:49], v[12:13] offset:1200
	global_load_dwordx4 v[248:251], v205, s[0:1] offset:480
	s_waitcnt vmcnt(6)
	v_pk_mul_f32 v[12:13], v[16:17], v[252:253]
	v_pk_mul_f32 v[2:3], v[2:3], v[254:255]
	v_pk_mul_f32 v[12:13], v[88:89], v[12:13]
	v_pk_mul_f32 v[2:3], v[30:31], v[2:3]
	v_cvt_pk_bf16_f32 v12, v12, v13
	v_cvt_pk_bf16_f32 v13, v2, v3
	flat_store_dwordx2 v[48:49], v[12:13] offset:1216
	v_pk_mul_f32 v[2:3], v[6:7], v[8:9] op_sel_hi:[1,0]
	s_waitcnt vmcnt(5)
	v_pk_mul_f32 v[0:1], v[0:1], v[242:243]
	v_pk_mul_f32 v[2:3], v[2:3], v[240:241]
	v_pk_mul_f32 v[0:1], v[4:5], v[0:1]
	v_pk_mul_f32 v[2:3], v[82:83], v[2:3]
	v_pk_mul_f32 v[4:5], v[72:73], v[8:9] op_sel_hi:[1,0]
	v_cvt_pk_bf16_f32 v2, v2, v3
	v_cvt_pk_bf16_f32 v3, v0, v1
	flat_store_dwordx2 v[48:49], v[2:3] offset:1232
	s_waitcnt vmcnt(4)
	v_pk_mul_f32 v[0:1], v[4:5], v[244:245]
	s_nop 0
	v_pk_mul_f32 v[0:1], v[78:79], v[0:1]
	v_lshlrev_b32_e32 v4, 16, v71
	v_cvt_pk_bf16_f32 v0, v0, v1
	v_mul_f32_e32 v1, 0xbfb8aa3b, v4
	v_exp_f32_e32 v1, v1
	v_and_b32_e32 v5, 0xffff0000, v71
	v_pk_mul_f32 v[2:3], v[10:11], v[246:247]
	v_pk_mul_f32 v[10:11], v[66:67], v[8:9] op_sel_hi:[1,0]
	v_add_f32_e32 v1, 1.0, v1
	v_rcp_f32_e32 v6, v1
	v_mul_f32_e32 v1, 0xbfb8aa3b, v5
	v_exp_f32_e32 v1, v1
	v_pk_mul_f32 v[8:9], v[64:65], v[8:9] op_sel_hi:[1,0]
	v_add_f32_e32 v1, 1.0, v1
	v_rcp_f32_e32 v7, v1
	s_nop 0
	v_pk_mul_f32 v[4:5], v[6:7], v[4:5]
	s_nop 0
	v_pk_mul_f32 v[2:3], v[4:5], v[2:3]
	v_lshlrev_b32_e32 v4, 16, v68
	v_cvt_pk_bf16_f32 v1, v2, v3
	flat_store_dwordx2 v[48:49], v[0:1] offset:1248
	v_and_b32_e32 v5, 0xffff0000, v68
	v_mul_f32_e32 v6, 0xbfb8aa3b, v4
	v_mul_f32_e32 v7, 0xbfb8aa3b, v5
	v_exp_f32_e32 v6, v6
	v_exp_f32_e32 v7, v7
	v_add_f32_e32 v6, 1.0, v6
	v_add_f32_e32 v7, 1.0, v7
	v_rcp_f32_e32 v6, v6
	v_rcp_f32_e32 v7, v7
	s_waitcnt vmcnt(3)
	v_pk_mul_f32 v[0:1], v[10:11], v[248:249]
	v_pk_mul_f32 v[4:5], v[6:7], v[4:5]
	v_pk_mul_f32 v[2:3], v[8:9], v[250:251]
	v_pk_mul_f32 v[0:1], v[4:5], v[0:1]
	v_lshlrev_b32_e32 v4, 16, v69
	v_cvt_pk_bf16_f32 v0, v0, v1
	v_mul_f32_e32 v1, 0xbfb8aa3b, v4
	v_exp_f32_e32 v1, v1
	v_and_b32_e32 v5, 0xffff0000, v69
	v_add_f32_e32 v1, 1.0, v1
	v_rcp_f32_e32 v6, v1
	v_mul_f32_e32 v1, 0xbfb8aa3b, v5
	v_exp_f32_e32 v1, v1
	s_nop 0
	v_add_f32_e32 v1, 1.0, v1
	v_rcp_f32_e32 v7, v1
	s_nop 0
	v_pk_mul_f32 v[4:5], v[6:7], v[4:5]
	s_nop 0
	v_pk_mul_f32 v[2:3], v[4:5], v[2:3]
	s_nop 0
	v_cvt_pk_bf16_f32 v1, v2, v3
	flat_store_dwordx2 v[48:49], v[0:1] offset:1264
	s_branch .LBB0_829

.LBB0_857:
	v_pk_add_f32 v[32:33], v[48:49], 0 op_sel_hi:[1,0]
	v_pk_add_f32 v[34:35], v[64:65], 0 op_sel_hi:[1,0]
	v_pk_add_f32 v[32:33], v[50:51], v[32:33]
	v_pk_add_f32 v[34:35], v[66:67], v[34:35]
	v_pk_add_f32 v[32:33], v[52:53], v[32:33]
	v_pk_add_f32 v[34:35], v[68:69], v[34:35]
	v_pk_add_f32 v[32:33], v[54:55], v[32:33]
	v_pk_add_f32 v[34:35], v[70:71], v[34:35]
	v_pk_add_f32 v[32:33], v[56:57], v[32:33]
	v_pk_add_f32 v[34:35], v[72:73], v[34:35]
	v_pk_add_f32 v[32:33], v[58:59], v[32:33]
	v_pk_add_f32 v[34:35], v[74:75], v[34:35]
	v_pk_add_f32 v[32:33], v[60:61], v[32:33]
	v_pk_add_f32 v[34:35], v[76:77], v[34:35]
	v_pk_add_f32 v[32:33], v[62:63], v[32:33]
	v_pk_add_f32 v[34:35], v[78:79], v[34:35]
	s_movk_i32 s2, 0x1400
	v_pk_add_f32 v[32:33], v[34:35], v[32:33]
	v_mov_b64_e32 v[34:35], s[14:15]
	v_mad_u64_u32 v[34:35], s[0:1], v116, s2, v[34:35]
	v_mov_b32_e32 v36, v35
	v_add_f32_e32 v32, v32, v33
	v_mad_u64_u32 v[36:37], s[0:1], v117, s2, v[36:37]
	v_add_f32_e32 v38, v96, v32
	v_mov_b32_e32 v35, v36
	v_lshl_add_u64 v[48:49], v[34:35], 0, s[40:41]
	ds_bpermute_b32 v34, v218, v38
	v_lshl_add_u64 v[32:33], v[118:119], 0, s[40:41]
	v_mov_b32_e32 v115, v193
	v_lshl_add_u64 v[32:33], v[32:33], 0, v[114:115]
	s_mov_b64 s[0:1], 0x1c00
	s_movk_i32 s8, 0x1000
	s_waitcnt lgkmcnt(0)
	v_add_f32_e32 v52, v38, v34
	v_lshl_add_u64 v[34:35], v[32:33], 0, s[0:1]
	v_add_co_u32_e32 v32, vcc, s8, v32
	s_nop 1
	v_addc_co_u32_e32 v33, vcc, 0, v33, vcc
	s_barrier
	s_barrier
	flat_load_dwordx2 v[50:51], v[32:33] offset:3072
	flat_load_dwordx2 v[46:47], v[34:35] offset:16
	flat_load_dwordx2 v[44:45], v[34:35] offset:32
	flat_load_dwordx2 v[42:43], v[34:35] offset:48
	flat_load_dwordx2 v[40:41], v[34:35] offset:64
	flat_load_dwordx2 v[38:39], v[34:35] offset:80
	flat_load_dwordx2 v[36:37], v[34:35] offset:96
	s_nop 0
	flat_load_dwordx2 v[34:35], v[34:35] offset:112
	v_rcp_f32_e32 v32, v52
	v_readlane_b32 s0, v239, 35
	s_add_i32 s16, s16, s0
	v_readlane_b32 s0, v239, 11
	s_add_i32 s11, s11, s0
	s_cmpk_gt_i32 s16, 0xff
	v_readlane_b32 s1, v239, 36
	s_waitcnt vmcnt(0) lgkmcnt(0)
	v_lshlrev_b32_e32 v52, 16, v50
	v_mul_f32_e32 v33, 0xbfb8aa3b, v52
	v_exp_f32_e32 v33, v33
	v_and_b32_e32 v53, 0xffff0000, v50
	v_add_f32_e32 v33, 1.0, v33
	v_rcp_f32_e32 v54, v33
	v_pk_mul_f32 v[0:1], v[0:1], v[32:33] op_sel_hi:[1,0]
	v_mul_f32_e32 v33, 0xbfb8aa3b, v53
	v_exp_f32_e32 v33, v33
	s_nop 0
	v_add_f32_e32 v33, 1.0, v33
	v_rcp_f32_e32 v55, v33
	s_nop 0
	v_pk_mul_f32 v[52:53], v[54:55], v[52:53]
	s_nop 0
	v_pk_mul_f32 v[0:1], v[0:1], v[52:53]
	s_nop 0
	v_cvt_pk_bf16_f32 v50, v0, v1
	v_lshlrev_b32_e32 v0, 16, v51
	v_mul_f32_e32 v33, 0xbfb8aa3b, v0
	v_exp_f32_e32 v33, v33
	v_and_b32_e32 v1, 0xffff0000, v51
	v_add_f32_e32 v33, 1.0, v33
	v_rcp_f32_e32 v52, v33
	v_pk_mul_f32 v[2:3], v[2:3], v[32:33] op_sel_hi:[1,0]
	v_mul_f32_e32 v33, 0xbfb8aa3b, v1
	v_exp_f32_e32 v33, v33
	s_nop 0
	v_add_f32_e32 v33, 1.0, v33
	v_rcp_f32_e32 v53, v33
	s_nop 0
	v_pk_mul_f32 v[0:1], v[52:53], v[0:1]
	s_nop 0
	v_pk_mul_f32 v[0:1], v[2:3], v[0:1]
	v_lshlrev_b32_e32 v2, 16, v46
	v_mul_f32_e32 v33, 0xbfb8aa3b, v2
	v_exp_f32_e32 v33, v33
	v_and_b32_e32 v3, 0xffff0000, v46
	v_cvt_pk_bf16_f32 v51, v0, v1
	v_lshl_add_u64 v[0:1], v[48:49], 0, v[114:115]
	v_add_f32_e32 v33, 1.0, v33
	v_rcp_f32_e32 v48, v33
	v_pk_mul_f32 v[4:5], v[4:5], v[32:33] op_sel_hi:[1,0]
	v_mul_f32_e32 v33, 0xbfb8aa3b, v3
	v_exp_f32_e32 v33, v33
	flat_store_dwordx2 v[0:1], v[50:51] offset:2048
	v_add_f32_e32 v33, 1.0, v33
	v_rcp_f32_e32 v49, v33
	v_pk_mul_f32 v[6:7], v[6:7], v[32:33] op_sel_hi:[1,0]
	v_pk_mul_f32 v[2:3], v[48:49], v[2:3]
	s_nop 0
	v_pk_mul_f32 v[2:3], v[4:5], v[2:3]
	v_lshlrev_b32_e32 v4, 16, v47
	v_cvt_pk_bf16_f32 v2, v2, v3
	v_mul_f32_e32 v3, 0xbfb8aa3b, v4
	v_exp_f32_e32 v3, v3
	v_and_b32_e32 v5, 0xffff0000, v47
	v_add_f32_e32 v3, 1.0, v3
	v_rcp_f32_e32 v46, v3
	v_mul_f32_e32 v3, 0xbfb8aa3b, v5
	v_exp_f32_e32 v3, v3
	s_nop 0
	v_add_f32_e32 v3, 1.0, v3
	v_rcp_f32_e32 v47, v3
	s_nop 0
	v_pk_mul_f32 v[4:5], v[46:47], v[4:5]
	s_nop 0
	v_pk_mul_f32 v[4:5], v[6:7], v[4:5]
	v_pk_mul_f32 v[6:7], v[8:9], v[32:33] op_sel_hi:[1,0]
	v_cvt_pk_bf16_f32 v3, v4, v5
	flat_store_dwordx2 v[0:1], v[2:3] offset:2064
	v_lshlrev_b32_e32 v2, 16, v44
	v_and_b32_e32 v3, 0xffff0000, v44
	v_mul_f32_e32 v4, 0xbfb8aa3b, v2
	v_mul_f32_e32 v5, 0xbfb8aa3b, v3
	v_exp_f32_e32 v4, v4
	v_exp_f32_e32 v5, v5
	v_pk_mul_f32 v[8:9], v[10:11], v[32:33] op_sel_hi:[1,0]
	v_add_f32_e32 v4, 1.0, v4
	v_add_f32_e32 v5, 1.0, v5
	v_rcp_f32_e32 v4, v4
	v_rcp_f32_e32 v5, v5
	s_nop 0
	v_pk_mul_f32 v[2:3], v[4:5], v[2:3]
	s_nop 0
	v_pk_mul_f32 v[2:3], v[6:7], v[2:3]
	v_lshlrev_b32_e32 v4, 16, v45
	v_cvt_pk_bf16_f32 v2, v2, v3
	v_mul_f32_e32 v3, 0xbfb8aa3b, v4
	v_exp_f32_e32 v3, v3
	v_and_b32_e32 v5, 0xffff0000, v45
	v_add_f32_e32 v3, 1.0, v3
	v_rcp_f32_e32 v6, v3
	v_mul_f32_e32 v3, 0xbfb8aa3b, v5
	v_exp_f32_e32 v3, v3
	s_nop 0
	v_add_f32_e32 v3, 1.0, v3
	v_rcp_f32_e32 v7, v3
	s_nop 0
	v_pk_mul_f32 v[4:5], v[6:7], v[4:5]
	s_nop 0
	v_pk_mul_f32 v[4:5], v[8:9], v[4:5]
	v_pk_mul_f32 v[6:7], v[12:13], v[32:33] op_sel_hi:[1,0]
	v_cvt_pk_bf16_f32 v3, v4, v5
	flat_store_dwordx2 v[0:1], v[2:3] offset:2080
	v_lshlrev_b32_e32 v2, 16, v42
	v_and_b32_e32 v3, 0xffff0000, v42
	v_mul_f32_e32 v4, 0xbfb8aa3b, v2
	v_mul_f32_e32 v5, 0xbfb8aa3b, v3
	v_exp_f32_e32 v4, v4
	v_exp_f32_e32 v5, v5
	v_pk_mul_f32 v[8:9], v[14:15], v[32:33] op_sel_hi:[1,0]
	v_add_f32_e32 v4, 1.0, v4
	v_add_f32_e32 v5, 1.0, v5
	v_rcp_f32_e32 v4, v4
	v_rcp_f32_e32 v5, v5
	s_nop 0
	v_pk_mul_f32 v[2:3], v[4:5], v[2:3]
	s_nop 0
	v_pk_mul_f32 v[2:3], v[6:7], v[2:3]
	v_lshlrev_b32_e32 v4, 16, v43
	v_cvt_pk_bf16_f32 v2, v2, v3
	v_mul_f32_e32 v3, 0xbfb8aa3b, v4
	v_exp_f32_e32 v3, v3
	v_and_b32_e32 v5, 0xffff0000, v43
	v_add_f32_e32 v3, 1.0, v3
	v_rcp_f32_e32 v6, v3
	v_mul_f32_e32 v3, 0xbfb8aa3b, v5
	v_exp_f32_e32 v3, v3
	s_nop 0
	v_add_f32_e32 v3, 1.0, v3
	v_rcp_f32_e32 v7, v3
	s_nop 0
	v_pk_mul_f32 v[4:5], v[6:7], v[4:5]
	s_nop 0
	v_pk_mul_f32 v[4:5], v[8:9], v[4:5]
	v_pk_mul_f32 v[6:7], v[16:17], v[32:33] op_sel_hi:[1,0]
	v_cvt_pk_bf16_f32 v3, v4, v5
	flat_store_dwordx2 v[0:1], v[2:3] offset:2096
	v_lshlrev_b32_e32 v2, 16, v40
	v_and_b32_e32 v3, 0xffff0000, v40
	v_mul_f32_e32 v4, 0xbfb8aa3b, v2
	v_mul_f32_e32 v5, 0xbfb8aa3b, v3
	v_exp_f32_e32 v4, v4
	v_exp_f32_e32 v5, v5
	v_pk_mul_f32 v[8:9], v[18:19], v[32:33] op_sel_hi:[1,0]
	v_add_f32_e32 v4, 1.0, v4
	v_add_f32_e32 v5, 1.0, v5
	v_rcp_f32_e32 v4, v4
	v_rcp_f32_e32 v5, v5
	s_nop 0
	v_pk_mul_f32 v[2:3], v[4:5], v[2:3]
	s_nop 0
	v_pk_mul_f32 v[2:3], v[6:7], v[2:3]
	v_lshlrev_b32_e32 v4, 16, v41
	v_cvt_pk_bf16_f32 v2, v2, v3
	v_mul_f32_e32 v3, 0xbfb8aa3b, v4
	v_exp_f32_e32 v3, v3
	v_and_b32_e32 v5, 0xffff0000, v41
	v_add_f32_e32 v3, 1.0, v3
	v_rcp_f32_e32 v6, v3
	v_mul_f32_e32 v3, 0xbfb8aa3b, v5
	v_exp_f32_e32 v3, v3
	s_nop 0
	v_add_f32_e32 v3, 1.0, v3
	v_rcp_f32_e32 v7, v3
	s_nop 0
	v_pk_mul_f32 v[4:5], v[6:7], v[4:5]
	s_nop 0
	v_pk_mul_f32 v[4:5], v[8:9], v[4:5]
	v_pk_mul_f32 v[6:7], v[20:21], v[32:33] op_sel_hi:[1,0]
	v_cvt_pk_bf16_f32 v3, v4, v5
	flat_store_dwordx2 v[0:1], v[2:3] offset:2112
	v_lshlrev_b32_e32 v2, 16, v38
	v_and_b32_e32 v3, 0xffff0000, v38
	v_mul_f32_e32 v4, 0xbfb8aa3b, v2
	v_mul_f32_e32 v5, 0xbfb8aa3b, v3
	v_exp_f32_e32 v4, v4
	v_exp_f32_e32 v5, v5
	v_pk_mul_f32 v[8:9], v[22:23], v[32:33] op_sel_hi:[1,0]
	v_add_f32_e32 v4, 1.0, v4
	v_add_f32_e32 v5, 1.0, v5
	v_rcp_f32_e32 v4, v4
	v_rcp_f32_e32 v5, v5
	s_nop 0
	v_pk_mul_f32 v[2:3], v[4:5], v[2:3]
	s_nop 0
	v_pk_mul_f32 v[2:3], v[6:7], v[2:3]
	v_lshlrev_b32_e32 v4, 16, v39
	v_cvt_pk_bf16_f32 v2, v2, v3
	v_mul_f32_e32 v3, 0xbfb8aa3b, v4
	v_exp_f32_e32 v3, v3
	v_and_b32_e32 v5, 0xffff0000, v39
	v_add_f32_e32 v3, 1.0, v3
	v_rcp_f32_e32 v6, v3
	v_mul_f32_e32 v3, 0xbfb8aa3b, v5
	v_exp_f32_e32 v3, v3
	s_nop 0
	v_add_f32_e32 v3, 1.0, v3
	v_rcp_f32_e32 v7, v3
	s_nop 0
	v_pk_mul_f32 v[4:5], v[6:7], v[4:5]
	s_nop 0
	v_pk_mul_f32 v[4:5], v[8:9], v[4:5]
	v_pk_mul_f32 v[6:7], v[24:25], v[32:33] op_sel_hi:[1,0]
	v_cvt_pk_bf16_f32 v3, v4, v5
	flat_store_dwordx2 v[0:1], v[2:3] offset:2128
	v_lshlrev_b32_e32 v2, 16, v36
	v_and_b32_e32 v3, 0xffff0000, v36
	v_mul_f32_e32 v4, 0xbfb8aa3b, v2
	v_mul_f32_e32 v5, 0xbfb8aa3b, v3
	v_exp_f32_e32 v4, v4
	v_exp_f32_e32 v5, v5
	v_pk_mul_f32 v[8:9], v[26:27], v[32:33] op_sel_hi:[1,0]
	v_add_f32_e32 v4, 1.0, v4
	v_add_f32_e32 v5, 1.0, v5
	v_rcp_f32_e32 v4, v4
	v_rcp_f32_e32 v5, v5
	s_nop 0
	v_pk_mul_f32 v[2:3], v[4:5], v[2:3]
	s_nop 0
	v_pk_mul_f32 v[2:3], v[6:7], v[2:3]
	v_lshlrev_b32_e32 v4, 16, v37
	v_cvt_pk_bf16_f32 v2, v2, v3
	v_mul_f32_e32 v3, 0xbfb8aa3b, v4
	v_exp_f32_e32 v3, v3
	v_and_b32_e32 v5, 0xffff0000, v37
	v_add_f32_e32 v3, 1.0, v3
	v_rcp_f32_e32 v6, v3
	v_mul_f32_e32 v3, 0xbfb8aa3b, v5
	v_exp_f32_e32 v3, v3
	s_nop 0
	v_add_f32_e32 v3, 1.0, v3
	v_rcp_f32_e32 v7, v3
	s_nop 0
	v_pk_mul_f32 v[4:5], v[6:7], v[4:5]
	s_nop 0
	v_pk_mul_f32 v[4:5], v[8:9], v[4:5]
	v_pk_mul_f32 v[6:7], v[28:29], v[32:33] op_sel_hi:[1,0]
	v_cvt_pk_bf16_f32 v3, v4, v5
	flat_store_dwordx2 v[0:1], v[2:3] offset:2144
	v_lshlrev_b32_e32 v2, 16, v34
	v_and_b32_e32 v3, 0xffff0000, v34
	v_mul_f32_e32 v4, 0xbfb8aa3b, v2
	v_mul_f32_e32 v5, 0xbfb8aa3b, v3
	v_exp_f32_e32 v4, v4
	v_exp_f32_e32 v5, v5
	v_pk_mul_f32 v[8:9], v[30:31], v[32:33] op_sel_hi:[1,0]
	v_add_f32_e32 v4, 1.0, v4
	v_add_f32_e32 v5, 1.0, v5
	v_rcp_f32_e32 v4, v4
	v_rcp_f32_e32 v5, v5
	s_nop 0
	v_pk_mul_f32 v[2:3], v[4:5], v[2:3]
	s_nop 0
	v_pk_mul_f32 v[2:3], v[6:7], v[2:3]
	v_lshlrev_b32_e32 v4, 16, v35
	v_cvt_pk_bf16_f32 v2, v2, v3
	v_mul_f32_e32 v3, 0xbfb8aa3b, v4
	v_exp_f32_e32 v3, v3
	v_and_b32_e32 v5, 0xffff0000, v35
	v_add_f32_e32 v3, 1.0, v3
	v_rcp_f32_e32 v6, v3
	v_mul_f32_e32 v3, 0xbfb8aa3b, v5
	v_exp_f32_e32 v3, v3
	s_nop 0
	v_add_f32_e32 v3, 1.0, v3
	v_rcp_f32_e32 v7, v3
	s_nop 0
	v_pk_mul_f32 v[4:5], v[6:7], v[4:5]
	s_nop 0
	v_pk_mul_f32 v[4:5], v[8:9], v[4:5]
	s_nop 0
	v_cvt_pk_bf16_f32 v3, v4, v5
	flat_store_dwordx2 v[0:1], v[2:3] offset:2160
	s_cbranch_scc1 .LBB0_880
.LBB0_858:
	s_ashr_i32 s0, s16, 3
	s_ashr_i32 s1, s0, 31
	s_lshl_b64 s[4:5], s[0:1], 8
	s_mul_i32 s3, s0, 0x208000
	s_mul_hi_i32 s2, s0, 0x208000
	s_add_u32 s3, s12, s3
	s_addc_u32 s2, s13, s2
	s_and_b32 s6, s11, 0x1c0
	s_lshl_b32 s40, s6, 1
	s_add_u32 s3, s3, s40
	v_mov_b32_e32 v41, v206
	s_addc_u32 s7, s2, 0
	s_add_u32 s2, s3, 0x1800
	v_ashrrev_i32_e32 v0, 31, v41
	v_lshrrev_b32_e32 v0, 29, v0
	s_addc_u32 s3, s7, 0
	s_lshl_b32 s6, s6, 15
	v_add_u32_e32 v2, v41, v0
	s_add_u32 s6, s85, s6
	v_ashrrev_i32_e32 v100, 3, v2
	v_and_b32_e32 v2, -8, v2
	s_addc_u32 s7, s82, 0
	s_lshl_b64 s[0:1], s[0:1], 9
	v_sub_u32_e32 v14, v41, v2
	s_add_u32 s0, s6, s0
	v_mov_b64_e32 v[0:1], s[2:3]
	v_lshlrev_b32_e32 v96, 3, v14
	v_ashrrev_i32_e32 v8, 3, v41
	s_addc_u32 s1, s7, s1
	v_mad_i64_i32 v[0:1], s[6:7], v100, s79, v[0:1]
	v_ashrrev_i32_e32 v97, 31, v96
	v_ashrrev_i32_e32 v9, 31, v8
	v_lshl_add_u64 v[42:43], v[96:97], 1, v[0:1]
	v_lshlrev_b64 v[0:1], 15, v[8:9]
	v_lshlrev_b32_e32 v9, 4, v41
	v_lshl_add_u64 v[0:1], s[0:1], 0, v[0:1]
	v_and_b32_e32 v2, 0x70, v9
	v_mov_b32_e32 v3, v193
	v_lshl_add_u64 v[10:11], v[0:1], 0, v[2:3]
	s_brev_b32 s0, 64
	v_add_co_u32_e32 v4, vcc, s0, v10
	v_mov_b64_e32 v[12:13], s[12:13]
	s_nop 0
	v_addc_co_u32_e32 v5, vcc, 0, v11, vcc
	flat_load_dwordx4 v[0:3], v[42:43]
	s_nop 0
	flat_load_dwordx4 v[4:7], v[4:5]
	v_lshl_add_u64 v[116:117], s[4:5], 0, v[112:113]
	v_lshrrev_b32_e32 v15, 1, v41
	v_lshlrev_b32_e32 v16, 3, v41
	v_mul_lo_u32 v8, v8, s80
	v_mad_u64_u32 v[118:119], s[0:1], v116, s79, v[12:13]
	v_and_b32_e32 v192, 16, v15
	v_and_b32_e32 v9, 0x60, v9
	v_and_b32_e32 v15, 8, v16
	v_add_u32_e32 v12, 0, v8
	v_mov_b32_e32 v8, v119
	v_add3_u32 v101, v12, v9, v15
	v_mad_u64_u32 v[8:9], s[0:1], v117, s79, v[8:9]
	v_mul_lo_u32 v9, v100, s80
	v_mov_b32_e32 v119, v8
	v_add_u32_e32 v12, 0, v9
	v_lshl_add_u64 v[8:9], v[118:119], 0, s[40:41]
	v_lshlrev_b32_e32 v13, 4, v14
	v_lshl_add_u64 v[8:9], v[8:9], 0, v[192:193]
	s_mov_b64 s[0:1], 0x1400
	v_add_u32_e32 v154, v12, v13
	v_lshl_add_u64 v[12:13], v[8:9], 0, s[0:1]
	v_add_co_u32_e32 v8, vcc, s8, v8
	s_mov_b32 s0, 0x82000
	s_nop 0
	v_addc_co_u32_e32 v9, vcc, 0, v9, vcc
	flat_load_dwordx4 v[88:91], v[12:13] offset:32
	flat_load_dwordx4 v[84:87], v[12:13] offset:64
	flat_load_dwordx4 v[92:95], v[8:9] offset:1024
	flat_load_dwordx4 v[80:83], v[12:13] offset:96
	v_add_co_u32_e32 v8, vcc, s0, v42
	v_add_u32_e32 v153, 0x4800, v101
	s_nop 0
	v_addc_co_u32_e32 v9, vcc, 0, v43, vcc
	s_mov_b64 s[0:1], 0x2000000
	v_lshl_add_u64 v[98:99], v[10:11], 0, s[0:1]
	v_and_b32_e32 v56, 31, v41
	v_add_u32_e32 v57, 0, v192
	v_mad_u32_u24 v152, v56, s80, v57
	s_mov_b32 s1, 0x104000
	v_add_co_u32_e32 v42, vcc, s1, v42
	v_readfirstlane_b32 s0, v41
	s_nop 0
	v_addc_co_u32_e32 v43, vcc, 0, v43, vcc
	v_mul_u32_u24_e32 v41, 0x90, v56
	v_add_u32_e32 v115, v57, v41
	s_cmpk_gt_i32 s0, 0xff
	s_cselect_b64 s[4:5], -1, 0
	s_cmpk_lt_i32 s0, 0x100
	v_mov_b32_e32 v40, 0
	s_waitcnt vmcnt(0) lgkmcnt(0)
	ds_write_b128 v154, v[0:3]
	ds_write2_b64 v153, v[4:5], v[6:7] offset1:2
	flat_load_dwordx4 v[0:3], v[8:9]
	flat_load_dwordx4 v[4:7], v[98:99] offset:128
	v_add_u32_e32 v8, 0x6800, v101
	s_waitcnt lgkmcnt(0)
	s_barrier
	s_barrier
	s_cselect_b64 s[0:1], -1, 0
	s_and_b64 vcc, exec, s[4:5]
	v_mov_b32_e32 v56, 0
	v_mov_b32_e32 v57, 0
	v_mov_b32_e32 v58, 0
	v_mov_b32_e32 v59, 0
	v_mov_b32_e32 v60, 0
	v_mov_b32_e32 v61, 0
	v_mov_b32_e32 v62, 0
	v_mov_b32_e32 v63, 0
	s_waitcnt vmcnt(0)
	ds_write_b128 v154, v[0:3] offset:9216
	ds_write2_b64 v8, v[4:5], v[6:7] offset0:128 offset1:130
	ds_read_b128 v[0:3], v152
	ds_read_b128 v[32:35], v152 offset:32
	ds_read_b128 v[16:19], v152 offset:4608
	ds_read_b128 v[36:39], v152 offset:4640
	s_waitcnt lgkmcnt(1)
	v_mfma_f32_32x32x16_bf16 v[16:31], v[16:19], v[92:95], 0
	s_waitcnt lgkmcnt(0)
	v_mfma_f32_32x32x16_bf16 v[16:31], v[36:39], v[88:91], v[16:31]
	ds_read_b128 v[36:39], v152 offset:64
	ds_read_b128 v[44:47], v152 offset:4672
	ds_read_b128 v[48:51], v152 offset:96
	ds_read_b128 v[52:55], v152 offset:4704
	flat_load_dwordx4 v[68:71], v[42:43]
	flat_load_dwordx4 v[64:67], v[98:99] offset:256
	v_mfma_f32_32x32x16_bf16 v[0:15], v[0:3], v[92:95], 0
	v_mfma_f32_32x32x16_bf16 v[0:15], v[32:35], v[88:91], v[0:15]
	v_mov_b32_e32 v32, 0
	v_mov_b32_e32 v33, 0
	v_mov_b32_e32 v34, 0
	v_mov_b32_e32 v35, 0
	s_waitcnt lgkmcnt(0)
	v_mfma_f32_32x32x16_bf16 v[0:15], v[36:39], v[84:87], v[0:15]
	v_mov_b32_e32 v36, 0
	v_mov_b32_e32 v37, 0
	v_mov_b32_e32 v38, 0
	v_mov_b32_e32 v39, 0
	v_mfma_f32_32x32x16_bf16 v[16:31], v[44:47], v[84:87], v[16:31]
	v_mov_b32_e32 v44, 0
	v_mov_b32_e32 v45, 0
	v_mov_b32_e32 v46, 0
	v_mov_b32_e32 v47, 0
	v_mfma_f32_32x32x16_bf16 v[0:15], v[48:51], v[80:83], v[0:15]
	v_mov_b32_e32 v48, 0
	v_mov_b32_e32 v49, 0
	v_mov_b32_e32 v50, 0
	v_mov_b32_e32 v51, 0
	v_mfma_f32_32x32x16_bf16 v[16:31], v[52:55], v[80:83], v[16:31]
	s_nop 6
	v_max_f32_e32 v41, v1, v1
	v_max_f32_e32 v42, v0, v0
	v_max_f32_e32 v41, v42, v41
	v_mov_b32_e32 v52, 0
	v_mov_b32_e32 v53, 0
	v_mov_b32_e32 v54, 0
	v_mov_b32_e32 v55, 0
	v_max3_f32 v43, v2, v3, v17
	v_max3_f32 v41, v41, v16, v18
	v_max3_f32 v42, v43, v6, v7
	v_max3_f32 v41, v41, v19, v4
	v_max3_f32 v42, v42, v22, v23
	v_max3_f32 v41, v41, v5, v20
	v_max3_f32 v42, v42, v10, v11
	v_max3_f32 v41, v41, v21, v8
	v_max3_f32 v42, v42, v26, v27
	v_max3_f32 v41, v41, v9, v24
	v_max3_f32 v42, v42, v14, v15
	v_max3_f32 v41, v41, v25, v12
	v_max3_f32 v42, v42, v30, v31
	v_max3_f32 v41, v41, v13, v28
	v_max3_f32 v41, v41, v29, v42
	v_mov_b32_e32 v42, v41
	s_nop 1
	v_permlane32_swap_b32_e32 v41, v42
	v_max_f32_e32 v42, v42, v42
	v_max_f32_e32 v41, v41, v41
	v_max_f32_e32 v155, v41, v42
	v_sub_f32_e32 v0, v0, v155
	v_sub_f32_e32 v16, v16, v155
	v_sub_f32_e32 v1, v1, v155
	v_sub_f32_e32 v17, v17, v155
	v_sub_f32_e32 v2, v2, v155
	v_sub_f32_e32 v18, v18, v155
	v_sub_f32_e32 v3, v3, v155
	v_sub_f32_e32 v19, v19, v155
	v_sub_f32_e32 v4, v4, v155
	v_sub_f32_e32 v20, v20, v155
	v_sub_f32_e32 v5, v5, v155
	v_sub_f32_e32 v21, v21, v155
	v_sub_f32_e32 v6, v6, v155
	v_sub_f32_e32 v22, v22, v155
	v_sub_f32_e32 v7, v7, v155
	v_sub_f32_e32 v23, v23, v155
	v_sub_f32_e32 v8, v8, v155
	v_sub_f32_e32 v24, v24, v155
	v_sub_f32_e32 v9, v9, v155
	v_sub_f32_e32 v25, v25, v155
	v_sub_f32_e32 v10, v10, v155
	v_sub_f32_e32 v26, v26, v155
	v_sub_f32_e32 v11, v11, v155
	v_sub_f32_e32 v27, v27, v155
	v_sub_f32_e32 v12, v12, v155
	v_sub_f32_e32 v28, v28, v155
	v_sub_f32_e32 v13, v13, v155
	v_sub_f32_e32 v29, v29, v155
	v_sub_f32_e32 v14, v14, v155
	v_sub_f32_e32 v30, v30, v155
	v_sub_f32_e32 v15, v15, v155
	v_sub_f32_e32 v31, v31, v155
	v_exp_f32_e32 v120, v0
	v_exp_f32_e32 v121, v1
	v_exp_f32_e32 v122, v16
	v_exp_f32_e32 v123, v17
	v_exp_f32_e32 v124, v2
	v_exp_f32_e32 v125, v3
	v_exp_f32_e32 v126, v18
	v_exp_f32_e32 v127, v19
	v_exp_f32_e32 v128, v4
	v_exp_f32_e32 v129, v5
	v_exp_f32_e32 v130, v20
	v_exp_f32_e32 v131, v21
	v_exp_f32_e32 v132, v6
	v_exp_f32_e32 v133, v7
	v_exp_f32_e32 v134, v22
	v_exp_f32_e32 v135, v23
	v_exp_f32_e32 v136, v8
	v_exp_f32_e32 v137, v9
	v_exp_f32_e32 v138, v24
	v_exp_f32_e32 v139, v25
	v_exp_f32_e32 v140, v10
	v_exp_f32_e32 v141, v11
	v_exp_f32_e32 v142, v26
	v_exp_f32_e32 v143, v27
	v_exp_f32_e32 v144, v12
	v_exp_f32_e32 v145, v13
	v_exp_f32_e32 v146, v28
	v_exp_f32_e32 v147, v29
	v_exp_f32_e32 v148, v14
	v_exp_f32_e32 v149, v15
	v_exp_f32_e32 v150, v30
	v_exp_f32_e32 v151, v31
	v_cvt_pk_bf16_f32 v104, v120, v121
	v_cvt_pk_bf16_f32 v105, v124, v125
	v_cvt_pk_bf16_f32 v106, v128, v129
	v_cvt_pk_bf16_f32 v107, v132, v133
	v_cvt_pk_bf16_f32 v72, v122, v123
	v_cvt_pk_bf16_f32 v73, v126, v127
	v_cvt_pk_bf16_f32 v74, v130, v131
	v_cvt_pk_bf16_f32 v75, v134, v135
	v_cvt_pk_bf16_f32 v108, v136, v137
	v_cvt_pk_bf16_f32 v109, v140, v141
	v_cvt_pk_bf16_f32 v110, v144, v145
	v_cvt_pk_bf16_f32 v111, v148, v149
	v_cvt_pk_bf16_f32 v76, v138, v139
	v_cvt_pk_bf16_f32 v77, v142, v143
	v_cvt_pk_bf16_f32 v78, v146, v147
	v_cvt_pk_bf16_f32 v79, v150, v151
	v_mov_b32_e32 v41, 0
	v_mov_b32_e32 v42, 0
	v_mov_b32_e32 v43, 0
	v_mov_b32_e32 v0, 0
	v_mov_b32_e32 v1, 0
	v_mov_b32_e32 v2, 0
	v_mov_b32_e32 v3, 0
	v_mov_b32_e32 v4, 0
	v_mov_b32_e32 v5, 0
	v_mov_b32_e32 v6, 0
	v_mov_b32_e32 v7, 0
	v_mov_b32_e32 v8, 0
	v_mov_b32_e32 v9, 0
	v_mov_b32_e32 v10, 0
	v_mov_b32_e32 v11, 0
	v_mov_b32_e32 v12, 0
	v_mov_b32_e32 v13, 0
	v_mov_b32_e32 v14, 0
	v_mov_b32_e32 v15, 0
	v_mov_b32_e32 v16, 0
	v_mov_b32_e32 v17, 0
	v_mov_b32_e32 v18, 0
	v_mov_b32_e32 v19, 0
	v_mov_b32_e32 v20, 0
	v_mov_b32_e32 v21, 0
	v_mov_b32_e32 v22, 0
	v_mov_b32_e32 v23, 0
	v_mov_b32_e32 v24, 0
	v_mov_b32_e32 v25, 0
	v_mov_b32_e32 v26, 0
	v_mov_b32_e32 v27, 0
	v_mov_b32_e32 v28, 0
	v_mov_b32_e32 v29, 0
	v_mov_b32_e32 v30, 0
	v_mov_b32_e32 v31, 0
	s_cbranch_vccnz .LBB0_860
	ds_read_b128 v[0:3], v115 offset:18432
	ds_read_b128 v[4:7], v115 offset:18464
	s_waitcnt lgkmcnt(0)
	v_mfma_f32_32x32x16_bf16 v[32:47], v[0:3], v[104:107], 0
	ds_read_b128 v[0:3], v115 offset:18496
	v_mfma_f32_32x32x16_bf16 v[32:47], v[4:7], v[108:111], v[32:47]
	s_waitcnt lgkmcnt(0)
	v_mfma_f32_32x32x16_bf16 v[32:47], v[0:3], v[72:75], v[32:47]
	ds_read_b128 v[0:3], v115 offset:18528
	s_waitcnt lgkmcnt(0)
	v_mfma_f32_32x32x16_bf16 v[32:47], v[0:3], v[76:79], v[32:47]
	ds_read_b128 v[0:3], v115 offset:23040
	s_waitcnt lgkmcnt(0)
	v_mfma_f32_32x32x16_bf16 v[48:63], v[0:3], v[104:107], 0
	ds_read_b128 v[0:3], v115 offset:23072
	s_nop 7
	v_mov_b32_e32 v4, v36
	v_mov_b32_e32 v5, v37
	v_mov_b32_e32 v6, v38
	v_mov_b32_e32 v7, v39
	v_mov_b32_e32 v8, v40
	v_mov_b32_e32 v9, v41
	s_waitcnt lgkmcnt(0)
	v_mfma_f32_32x32x16_bf16 v[48:63], v[0:3], v[108:111], v[48:63]
	ds_read_b128 v[0:3], v115 offset:23104
	v_mov_b32_e32 v10, v42
	v_mov_b32_e32 v11, v43
	v_mov_b32_e32 v12, v44
	v_mov_b32_e32 v13, v45
	v_mov_b32_e32 v14, v46
	v_mov_b32_e32 v15, v47
	s_waitcnt lgkmcnt(0)
	v_mfma_f32_32x32x16_bf16 v[48:63], v[0:3], v[72:75], v[48:63]
	ds_read_b128 v[0:3], v115 offset:23136
	s_waitcnt lgkmcnt(0)
	v_mfma_f32_32x32x16_bf16 v[48:63], v[0:3], v[76:79], v[48:63]
	v_mov_b32_e32 v0, v32
	v_mov_b32_e32 v1, v33
	v_mov_b32_e32 v2, v34
	v_mov_b32_e32 v3, v35
	s_nop 7
	v_mov_b32_e32 v16, v48
	v_mov_b32_e32 v17, v49
	v_mov_b32_e32 v18, v50
	v_mov_b32_e32 v19, v51
	v_mov_b32_e32 v20, v52
	v_mov_b32_e32 v21, v53
	v_mov_b32_e32 v22, v54
	v_mov_b32_e32 v23, v55
	v_mov_b32_e32 v24, v56
	v_mov_b32_e32 v25, v57
	v_mov_b32_e32 v26, v58
	v_mov_b32_e32 v27, v59
	v_mov_b32_e32 v28, v60
	v_mov_b32_e32 v29, v61
	v_mov_b32_e32 v30, v62
	v_mov_b32_e32 v31, v63
.LBB0_860:
	v_mad_i64_i32 v[102:103], s[6:7], v100, s79, 0
	s_waitcnt lgkmcnt(0)
	s_barrier
	s_barrier
	s_waitcnt vmcnt(0)
	ds_write_b128 v154, v[68:71]
	v_add_u32_e32 v68, 0x9000, v101
	ds_write2_b64 v68, v[64:65], v[66:67] offset1:2
	v_lshl_add_u64 v[64:65], s[2:3], 0, v[102:103]
	v_lshl_add_u64 v[64:65], v[96:97], 1, v[64:65]
	v_add_co_u32_e32 v64, vcc, 0x186000, v64
	s_nop 1
	v_addc_co_u32_e32 v65, vcc, 0, v65, vcc
	flat_load_dwordx4 v[100:103], v[64:65]
	s_nop 0
	flat_load_dwordx4 v[96:99], v[98:99] offset:384
	v_cndmask_b32_e64 v64, 0, 1, s[4:5]
	v_cmp_ne_u32_e64 s[6:7], 1, v64
	s_andn2_b64 vcc, exec, s[4:5]
	s_cbranch_vccnz .LBB0_862
	ds_read_b128 v[0:3], v115 offset:18432
	ds_read_b128 v[4:7], v115 offset:18464
	s_waitcnt lgkmcnt(0)
	v_mfma_f32_32x32x16_bf16 v[32:47], v[0:3], v[104:107], v[32:47]
	v_mfma_f32_32x32x16_bf16 v[32:47], v[4:7], v[108:111], v[32:47]
	ds_read_b128 v[0:3], v115 offset:18496
	ds_read_b128 v[4:7], v115 offset:18528
	s_waitcnt lgkmcnt(0)
	v_mfma_f32_32x32x16_bf16 v[32:47], v[0:3], v[72:75], v[32:47]
	v_mfma_f32_32x32x16_bf16 v[32:47], v[4:7], v[76:79], v[32:47]
	ds_read_b128 v[0:3], v115 offset:23040
	ds_read_b128 v[4:7], v115 offset:23072
	s_waitcnt lgkmcnt(0)
	v_mfma_f32_32x32x16_bf16 v[48:63], v[0:3], v[104:107], v[48:63]
	v_mfma_f32_32x32x16_bf16 v[48:63], v[4:7], v[108:111], v[48:63]
	ds_read_b128 v[0:3], v115 offset:23104
	ds_read_b128 v[4:7], v115 offset:23136
	s_waitcnt lgkmcnt(0)
	v_mfma_f32_32x32x16_bf16 v[48:63], v[0:3], v[72:75], v[48:63]
	v_mfma_f32_32x32x16_bf16 v[48:63], v[4:7], v[76:79], v[48:63]
	s_nop 1
	v_mov_b64_e32 v[0:1], v[32:33]
	v_mov_b64_e32 v[2:3], v[34:35]
	v_mov_b64_e32 v[4:5], v[36:37]
	v_mov_b64_e32 v[6:7], v[38:39]
	v_mov_b64_e32 v[8:9], v[40:41]
	v_mov_b64_e32 v[10:11], v[42:43]
	v_mov_b64_e32 v[12:13], v[44:45]
	v_mov_b64_e32 v[14:15], v[46:47]
	s_nop 1
	v_mov_b64_e32 v[16:17], v[48:49]
	v_mov_b64_e32 v[18:19], v[50:51]
	v_mov_b64_e32 v[20:21], v[52:53]
	v_mov_b64_e32 v[22:23], v[54:55]
	v_mov_b64_e32 v[24:25], v[56:57]
	v_mov_b64_e32 v[26:27], v[58:59]
	v_mov_b64_e32 v[28:29], v[60:61]
	v_mov_b64_e32 v[30:31], v[62:63]

.LBB0_866:
	s_waitcnt lgkmcnt(0)
	s_barrier
	s_barrier
	s_and_b64 vcc, exec, s[6:7]
	s_waitcnt vmcnt(0)
	ds_write_b128 v154, v[100:103] offset:9216
	ds_write2_b64 v153, v[96:97], v[98:99] offset1:2
	s_cbranch_vccnz .LBB0_868
	ds_read_b128 v[96:99], v115 offset:27648
	s_waitcnt lgkmcnt(0)
	v_mfma_f32_32x32x16_bf16 v[0:15], v[96:99], v[38:41], v[0:15]
	ds_read_b128 v[96:99], v115 offset:27680
	s_waitcnt lgkmcnt(0)
	v_mfma_f32_32x32x16_bf16 v[0:15], v[96:99], v[46:49], v[0:15]
	ds_read_b128 v[96:99], v115 offset:27712
	s_waitcnt lgkmcnt(0)
	v_mfma_f32_32x32x16_bf16 v[0:15], v[96:99], v[34:37], v[0:15]
	ds_read_b128 v[96:99], v115 offset:27744
	s_waitcnt lgkmcnt(0)
	v_mfma_f32_32x32x16_bf16 v[0:15], v[96:99], v[42:45], v[0:15]
	ds_read_b128 v[96:99], v115 offset:32256
	s_waitcnt lgkmcnt(0)
	v_mfma_f32_32x32x16_bf16 v[16:31], v[96:99], v[38:41], v[16:31]
	ds_read_b128 v[38:41], v115 offset:32288
	s_waitcnt lgkmcnt(0)
	v_mfma_f32_32x32x16_bf16 v[16:31], v[38:41], v[46:49], v[16:31]
	ds_read_b128 v[38:41], v115 offset:32320
	s_waitcnt lgkmcnt(0)
	v_mfma_f32_32x32x16_bf16 v[16:31], v[38:41], v[34:37], v[16:31]
	ds_read_b128 v[34:37], v115 offset:32352
	s_waitcnt lgkmcnt(0)
	v_mfma_f32_32x32x16_bf16 v[16:31], v[34:37], v[42:45], v[16:31]

.LBB0_872:
	s_waitcnt lgkmcnt(0)
	s_barrier
	s_barrier
	s_and_b64 vcc, exec, s[6:7]
	s_cbranch_vccnz .LBB0_874
	ds_read_b128 v[122:125], v115 offset:36864
	s_waitcnt lgkmcnt(0)
	v_mfma_f32_32x32x16_bf16 v[0:15], v[122:125], v[52:55], v[0:15]
	ds_read_b128 v[122:125], v115 offset:36896
	s_waitcnt lgkmcnt(0)
	v_mfma_f32_32x32x16_bf16 v[0:15], v[122:125], v[60:63], v[0:15]
	ds_read_b128 v[122:125], v115 offset:36928
	s_waitcnt lgkmcnt(0)
	v_mfma_f32_32x32x16_bf16 v[0:15], v[122:125], v[48:51], v[0:15]
	ds_read_b128 v[122:125], v115 offset:36960
	s_waitcnt lgkmcnt(0)
	v_mfma_f32_32x32x16_bf16 v[0:15], v[122:125], v[56:59], v[0:15]
	ds_read_b128 v[122:125], v115 offset:41472
	s_waitcnt lgkmcnt(0)
	v_mfma_f32_32x32x16_bf16 v[16:31], v[122:125], v[52:55], v[16:31]
	ds_read_b128 v[52:55], v115 offset:41504
	s_waitcnt lgkmcnt(0)
	v_mfma_f32_32x32x16_bf16 v[16:31], v[52:55], v[60:63], v[16:31]
	ds_read_b128 v[52:55], v115 offset:41536
	s_waitcnt lgkmcnt(0)
	v_mfma_f32_32x32x16_bf16 v[16:31], v[52:55], v[48:51], v[16:31]
	ds_read_b128 v[48:51], v115 offset:41568
	s_waitcnt lgkmcnt(0)
	v_mfma_f32_32x32x16_bf16 v[16:31], v[48:51], v[56:59], v[16:31]

.LBB0_878:
	s_waitcnt lgkmcnt(0)
	s_barrier
	s_barrier
	s_and_b64 vcc, exec, s[6:7]
	s_cbranch_vccnz .LBB0_857
	ds_read_b128 v[80:83], v115 offset:18432
	s_waitcnt lgkmcnt(0)
	v_mfma_f32_32x32x16_bf16 v[0:15], v[80:83], v[36:39], v[0:15]
	ds_read_b128 v[80:83], v115 offset:18464
	s_waitcnt lgkmcnt(0)
	v_mfma_f32_32x32x16_bf16 v[0:15], v[80:83], v[44:47], v[0:15]
	ds_read_b128 v[80:83], v115 offset:18496
	s_waitcnt lgkmcnt(0)
	v_mfma_f32_32x32x16_bf16 v[0:15], v[80:83], v[32:35], v[0:15]
	ds_read_b128 v[80:83], v115 offset:18528
	s_waitcnt lgkmcnt(0)
	v_mfma_f32_32x32x16_bf16 v[0:15], v[80:83], v[40:43], v[0:15]
	ds_read_b128 v[80:83], v115 offset:23040
	s_waitcnt lgkmcnt(0)
	v_mfma_f32_32x32x16_bf16 v[16:31], v[80:83], v[36:39], v[16:31]
	ds_read_b128 v[36:39], v115 offset:23072
	s_waitcnt lgkmcnt(0)
	v_mfma_f32_32x32x16_bf16 v[16:31], v[36:39], v[44:47], v[16:31]
	ds_read_b128 v[36:39], v115 offset:23104
	s_waitcnt lgkmcnt(0)
	v_mfma_f32_32x32x16_bf16 v[16:31], v[36:39], v[32:35], v[16:31]
	ds_read_b128 v[32:35], v115 offset:23136
	s_waitcnt lgkmcnt(0)
	v_mfma_f32_32x32x16_bf16 v[16:31], v[32:35], v[40:43], v[16:31]
	s_branch .LBB0_857
